# K-loop load segments: LDS-DMA loads issued first (one ds_read as M0-hazard separator each), fragment reads after the last DMA of the segment
# baseline (speedup 1.0000x reference)
; #define PG8_STAGEA(bufoff, gbase, voff) PG8_STAGE_X(bufoff, gbase, voff, AUXA)
; #define PG8_STAGEB(bufoff, gbase, voff) PG8_STAGE_X(bufoff, gbase, voff, AUXB)
; #define PG8_LDA(dst, b, h) do { _Pragma("unroll") for (int m = 0; m < 4; ++m) _Pragma("unroll") for (int k = 0; k < 2; ++k) dst[m][k] = *(const PG8_LAS bf16x8*)(lds + PG8_SA(b, h) + aoff + m * 2048 + k * 1024); } while (0)
; #define PG8_LDB(dst, b, h) do { _Pragma("unroll") for (int n = 0; n < 2; ++n) _Pragma("unroll") for (int k = 0; k < 2; ++k) dst[n][k] = *(const PG8_LAS bf16x8*)(lds + PG8_SB(b, h) + boff + n * 2048 + k * 1024); } while (0)
; #define PG8_MMA(ai, bj, At, Bt) do { if (GEMM_PRIO_MODE == 0) __builtin_amdgcn_s_setprio(1); PG8_MMA_LOOPS \
;         acc[ai][bj][m][n] = __builtin_amdgcn_mfma_f32_16x16x32_bf16(Bt[n][k], At[m][k], acc[ai][bj][m][n], 0, 0, 0); if (GEMM_PRIO_MODE == 0) __builtin_amdgcn_s_setprio(0); } while (0)
; #define PG8_WAIT_V(n) asm volatile("s_waitcnt vmcnt(" #n ")" ::: "memory")
; #define PG8_WAIT_VR(n, nr, flag) asm volatile("s_cmp_eq_u32 %0, 0\n\ts_cbranch_scc1 .Lpg8s%=\n\ts_waitcnt vmcnt(" #nr ")\n\ts_branch .Lpg8d%=\n.Lpg8s%=:\n\ts_waitcnt vmcnt(" #n ")\n.Lpg8d%=:" :: "s"(flag) : "memory", "scc")
; #define PG8_WAIT_L(n) asm volatile("s_waitcnt lgkmcnt(" #n ")" ::: "memory")
; #define PG8_BAR __builtin_amdgcn_s_barrier()
; #define PG8_SCHED __builtin_amdgcn_sched_barrier(0)
;     ...
;             PG8_LDB(B0, 0, 0); PG8_LDB(B1, 0, 1); PG8_SCHED; PG8_LDA(At, 0, 0); PG8_STAGEA(PG8_SA(1, 1), a1 + hstepA, voffA);
;     ...
;             const int relax = __builtin_amdgcn_readfirstlane((t == 0 && ui > 0) ? 1 : 0);
;             PG8_WAIT_VR(8, 24, relax); PG8_WAIT_L(0); PG8_BAR; PG8_MMA(0, 0, At, B0); PG8_MMA(0, 1, At, B1); PG8_BAR; PG8_SCHED;
;     ...
;             PG8_WAIT_V(8); PG8_WAIT_L(0); PG8_BAR; PG8_MMA(0, 0, At, B0); PG8_MMA(0, 1, At, B1); PG8_BAR; PG8_SCHED;
;     ...
;             PG8_LDA(At, 0, 1); PG8_STAGEB(PG8_SB(0, 0), b2, voffB); PG8_STAGEB(PG8_SB(0, 1), b2 + hstepB, voffB); PG8_STAGEA(PG8_SA(0, 0), a2, voffA);
;     ...
;             PG8_WAIT_VR(8, 24, relax); PG8_WAIT_L(0); PG8_BAR; PG8_MMA(1, 0, At, B0); PG8_MMA(1, 1, At, B1); PG8_BAR; PG8_SCHED;
;     ...
;             PG8_WAIT_V(8); PG8_WAIT_L(0); PG8_BAR; PG8_MMA(1, 0, At, B0); PG8_MMA(1, 1, At, B1); PG8_BAR; PG8_SCHED;
.LBB0_129:
	s_add_u32 s10, s8, 0xfff00080
	s_addc_u32 s11, s9, -1
	s_add_i32 s18, 0, 0x10000
	s_cmp_eq_u32 s27, 60
	s_cselect_b32 s15, s4, s11
	s_cselect_b32 s14, s5, s10
	s_cselect_b32 s11, s16, s1
	s_cselect_b32 s10, s17, s0
	s_add_i32 s20, 0, 0x14000
	s_waitcnt lgkmcnt(0)
	s_add_i32 m0, s51, 0xc000
	ds_read_b128 v[130:133], v226
	global_load_lds_dwordx4 v148, s[8:9]
	s_add_i32 m0, s51, 0xe000
	ds_read_b128 v[134:137], v226 offset:1024
	global_load_lds_dwordx4 v150, s[8:9]
	ds_read_b128 v[152:155], v226 offset:2048
	ds_read_b128 v[156:159], v226 offset:3072
	ds_read_b128 v[160:163], v226 offset:16384
	ds_read_b128 v[174:177], v226 offset:17408
	ds_read_b128 v[178:181], v226 offset:18432
	ds_read_b128 v[182:185], v226 offset:19456
	ds_read_b128 v[186:189], v172
	ds_read_b128 v[190:193], v172 offset:1024
	ds_read_b128 v[194:197], v172 offset:2048
	ds_read_b128 v[198:201], v172 offset:3072
	ds_read_b128 v[202:205], v172 offset:4096
	ds_read_b128 v[206:209], v172 offset:5120
	ds_read_b128 v[210:213], v172 offset:6144
	ds_read_b128 v[214:217], v172 offset:7168
	s_waitcnt vmcnt(8) lgkmcnt(0)
	s_nop 0
	s_barrier
	v_mfma_f32_16x16x32_bf16 v[126:129], v[130:133], v[186:189], v[126:129]
	v_mfma_f32_16x16x32_bf16 v[122:125], v[152:155], v[186:189], v[122:125]
	v_mfma_f32_16x16x32_bf16 v[110:113], v[130:133], v[194:197], v[110:113]
	v_mfma_f32_16x16x32_bf16 v[106:109], v[152:155], v[194:197], v[106:109]
	v_mfma_f32_16x16x32_bf16 v[94:97], v[130:133], v[202:205], v[94:97]
	v_mfma_f32_16x16x32_bf16 v[90:93], v[152:155], v[202:205], v[90:93]
	v_mfma_f32_16x16x32_bf16 v[78:81], v[130:133], v[210:213], v[78:81]
	v_mfma_f32_16x16x32_bf16 v[74:77], v[152:155], v[210:213], v[74:77]
	v_mfma_f32_16x16x32_bf16 v[126:129], v[134:137], v[190:193], v[126:129]
	v_mfma_f32_16x16x32_bf16 v[122:125], v[156:159], v[190:193], v[122:125]
	v_mfma_f32_16x16x32_bf16 v[110:113], v[134:137], v[198:201], v[110:113]
	v_mfma_f32_16x16x32_bf16 v[106:109], v[156:159], v[198:201], v[106:109]
	v_mfma_f32_16x16x32_bf16 v[94:97], v[134:137], v[206:209], v[94:97]
	v_mfma_f32_16x16x32_bf16 v[90:93], v[156:159], v[206:209], v[90:93]
	v_mfma_f32_16x16x32_bf16 v[78:81], v[134:137], v[214:217], v[78:81]
	v_mfma_f32_16x16x32_bf16 v[74:77], v[156:159], v[214:217], v[74:77]
	v_mfma_f32_16x16x32_bf16 v[118:121], v[160:163], v[186:189], v[118:121]
	v_mfma_f32_16x16x32_bf16 v[114:117], v[178:181], v[186:189], v[114:117]
	v_mfma_f32_16x16x32_bf16 v[102:105], v[160:163], v[194:197], v[102:105]
	v_mfma_f32_16x16x32_bf16 v[98:101], v[178:181], v[194:197], v[98:101]
	v_mfma_f32_16x16x32_bf16 v[86:89], v[160:163], v[202:205], v[86:89]
	v_mfma_f32_16x16x32_bf16 v[82:85], v[178:181], v[202:205], v[82:85]
	v_mfma_f32_16x16x32_bf16 v[70:73], v[160:163], v[210:213], v[70:73]
	v_mfma_f32_16x16x32_bf16 v[66:69], v[178:181], v[210:213], v[66:69]
	v_mfma_f32_16x16x32_bf16 v[118:121], v[174:177], v[190:193], v[118:121]
	v_mfma_f32_16x16x32_bf16 v[114:117], v[182:185], v[190:193], v[114:117]
	v_mfma_f32_16x16x32_bf16 v[102:105], v[174:177], v[198:201], v[102:105]
	v_mfma_f32_16x16x32_bf16 v[98:101], v[182:185], v[198:201], v[98:101]
	v_mfma_f32_16x16x32_bf16 v[86:89], v[174:177], v[206:209], v[86:89]
	v_mfma_f32_16x16x32_bf16 v[82:85], v[182:185], v[206:209], v[82:85]
	v_mfma_f32_16x16x32_bf16 v[70:73], v[174:177], v[214:217], v[70:73]
	v_mfma_f32_16x16x32_bf16 v[66:69], v[182:185], v[214:217], v[66:69]
	s_barrier
	s_add_i32 s18, s18, s42
	s_mov_b32 m0, s18
	s_add_u32 s100, s14, 0x80
	s_addc_u32 s101, s15, 0
	global_load_lds_dwordx4 v142, s[10:11]
	s_add_i32 m0, s18, 0x2000
	s_add_u32 s18, s10, 0x100000
	s_addc_u32 s19, s11, 0
	s_add_i32 s20, s20, s42
	global_load_lds_dwordx4 v138, s[10:11]
	s_mov_b32 m0, s20
	ds_read_b128 v[186:189], v172 offset:16384
	global_load_lds_dwordx4 v142, s[18:19]
	s_add_i32 m0, s20, 0x2000
	ds_read_b128 v[190:193], v172 offset:17408
	global_load_lds_dwordx4 v138, s[18:19]
	s_mov_b32 m0, s51
	ds_read_b128 v[194:197], v172 offset:18432
	global_load_lds_dwordx4 v144, s[14:15]
	s_mov_b32 m0, s68
	ds_read_b128 v[198:201], v172 offset:19456
	global_load_lds_dwordx4 v140, s[14:15]
	ds_read_b128 v[214:217], v172 offset:23552
	ds_read_b128 v[210:213], v172 offset:22528
	ds_read_b128 v[206:209], v172 offset:21504
	ds_read_b128 v[202:205], v172 offset:20480
	s_waitcnt vmcnt(8) lgkmcnt(0)
	s_nop 0
	s_barrier
	v_mfma_f32_16x16x32_bf16 v[62:65], v[130:133], v[186:189], v[62:65]
	v_mfma_f32_16x16x32_bf16 v[58:61], v[152:155], v[186:189], v[58:61]
	v_mfma_f32_16x16x32_bf16 v[46:49], v[130:133], v[194:197], v[46:49]
	v_mfma_f32_16x16x32_bf16 v[42:45], v[152:155], v[194:197], v[42:45]
	v_mfma_f32_16x16x32_bf16 v[30:33], v[130:133], v[202:205], v[30:33]
	v_mfma_f32_16x16x32_bf16 v[26:29], v[152:155], v[202:205], v[26:29]
	v_mfma_f32_16x16x32_bf16 v[12:15], v[130:133], v[210:213], v[12:15]
	v_mfma_f32_16x16x32_bf16 v[8:11], v[152:155], v[210:213], v[8:11]
	v_mfma_f32_16x16x32_bf16 v[62:65], v[134:137], v[190:193], v[62:65]
	v_mfma_f32_16x16x32_bf16 v[58:61], v[156:159], v[190:193], v[58:61]
	v_mfma_f32_16x16x32_bf16 v[46:49], v[134:137], v[198:201], v[46:49]
	v_mfma_f32_16x16x32_bf16 v[42:45], v[156:159], v[198:201], v[42:45]
	v_mfma_f32_16x16x32_bf16 v[30:33], v[134:137], v[206:209], v[30:33]
	v_mfma_f32_16x16x32_bf16 v[26:29], v[156:159], v[206:209], v[26:29]
	v_mfma_f32_16x16x32_bf16 v[12:15], v[134:137], v[214:217], v[12:15]
	v_mfma_f32_16x16x32_bf16 v[8:11], v[156:159], v[214:217], v[8:11]
	v_mfma_f32_16x16x32_bf16 v[54:57], v[160:163], v[186:189], v[54:57]
	v_mfma_f32_16x16x32_bf16 v[50:53], v[178:181], v[186:189], v[50:53]
	v_mfma_f32_16x16x32_bf16 v[38:41], v[160:163], v[194:197], v[38:41]
	v_mfma_f32_16x16x32_bf16 v[34:37], v[178:181], v[194:197], v[34:37]
	v_mfma_f32_16x16x32_bf16 v[22:25], v[160:163], v[202:205], v[22:25]
	v_mfma_f32_16x16x32_bf16 v[18:21], v[178:181], v[202:205], v[18:21]
	v_mfma_f32_16x16x32_bf16 v[4:7], v[160:163], v[210:213], v[4:7]
	v_mfma_f32_16x16x32_bf16 v[0:3], v[178:181], v[210:213], v[0:3]
	v_mfma_f32_16x16x32_bf16 v[54:57], v[174:177], v[190:193], v[54:57]
	v_mfma_f32_16x16x32_bf16 v[50:53], v[182:185], v[190:193], v[50:53]
	v_mfma_f32_16x16x32_bf16 v[38:41], v[174:177], v[198:201], v[38:41]
	v_mfma_f32_16x16x32_bf16 v[34:37], v[182:185], v[198:201], v[34:37]
	v_mfma_f32_16x16x32_bf16 v[22:25], v[174:177], v[206:209], v[22:25]
	v_mfma_f32_16x16x32_bf16 v[18:21], v[182:185], v[206:209], v[18:21]
	v_mfma_f32_16x16x32_bf16 v[4:7], v[174:177], v[214:217], v[4:7]
	v_mfma_f32_16x16x32_bf16 v[0:3], v[182:185], v[214:217], v[0:3]
	s_barrier
; #define PG8_STAGEA(bufoff, gbase, voff) PG8_STAGE_X(bufoff, gbase, voff, AUXA)
; #define PG8_STAGEB(bufoff, gbase, voff) PG8_STAGE_X(bufoff, gbase, voff, AUXB)
; #define PG8_LDA(dst, b, h) do { _Pragma("unroll") for (int m = 0; m < 4; ++m) _Pragma("unroll") for (int k = 0; k < 2; ++k) dst[m][k] = *(const PG8_LAS bf16x8*)(lds + PG8_SA(b, h) + aoff + m * 2048 + k * 1024); } while (0)
; #define PG8_LDB(dst, b, h) do { _Pragma("unroll") for (int n = 0; n < 2; ++n) _Pragma("unroll") for (int k = 0; k < 2; ++k) dst[n][k] = *(const PG8_LAS bf16x8*)(lds + PG8_SB(b, h) + boff + n * 2048 + k * 1024); } while (0)
; #define PG8_MMA(ai, bj, At, Bt) do { if (GEMM_PRIO_MODE == 0) __builtin_amdgcn_s_setprio(1); PG8_MMA_LOOPS \
;         acc[ai][bj][m][n] = __builtin_amdgcn_mfma_f32_16x16x32_bf16(Bt[n][k], At[m][k], acc[ai][bj][m][n], 0, 0, 0); if (GEMM_PRIO_MODE == 0) __builtin_amdgcn_s_setprio(0); } while (0)
; #define PG8_WAIT_V(n) asm volatile("s_waitcnt vmcnt(" #n ")" ::: "memory")
; #define PG8_WAIT_L(n) asm volatile("s_waitcnt lgkmcnt(" #n ")" ::: "memory")
; #define PG8_BAR __builtin_amdgcn_s_barrier()
; #define PG8_SCHED __builtin_amdgcn_sched_barrier(0)
;     ...
;             PG8_LDB(B0, 1, 0); PG8_LDB(B1, 1, 1); PG8_SCHED; PG8_LDA(At, 1, 0); PG8_STAGEA(PG8_SA(0, 1), a2 + hstepA, voffA);
;             PG8_WAIT_V(8); PG8_WAIT_L(0); PG8_BAR; PG8_MMA(0, 0, At, B0); PG8_MMA(0, 1, At, B1); PG8_BAR; PG8_SCHED;
;             PG8_LDA(At, 1, 1); PG8_STAGEB(PG8_SB(1, 0), b3, voffB); PG8_STAGEB(PG8_SB(1, 1), b3 + hstepB, voffB); PG8_STAGEA(PG8_SA(1, 0), a3, voffA);
;             PG8_WAIT_V(8); PG8_WAIT_L(0); PG8_BAR; PG8_MMA(1, 0, At, B0); PG8_MMA(1, 1, At, B1); PG8_BAR; PG8_SCHED;
	s_add_i32 s18, 0, 0x18000
	s_add_i32 s19, 0, 0x1c000
	s_add_u32 s14, s14, 0x100000
	s_addc_u32 s15, s15, 0
	s_mov_b32 m0, s69
	ds_read_b128 v[130:133], v226 offset:32768
	global_load_lds_dwordx4 v144, s[14:15]
	s_mov_b32 m0, s72
	ds_read_b128 v[134:137], v226 offset:33792
	global_load_lds_dwordx4 v140, s[14:15]
	ds_read_b128 v[152:155], v226 offset:34816
	ds_read_b128 v[156:159], v226 offset:35840
	ds_read_b128 v[160:163], v226 offset:49152
	ds_read_b128 v[174:177], v226 offset:50176
	ds_read_b128 v[178:181], v226 offset:51200
	ds_read_b128 v[182:185], v226 offset:52224
	ds_read_b128 v[186:189], v172 offset:32768
	ds_read_b128 v[190:193], v172 offset:33792
	ds_read_b128 v[194:197], v172 offset:34816
	ds_read_b128 v[198:201], v172 offset:35840
	ds_read_b128 v[202:205], v172 offset:36864
	ds_read_b128 v[206:209], v172 offset:37888
	ds_read_b128 v[210:213], v172 offset:38912
	ds_read_b128 v[214:217], v172 offset:39936
	s_waitcnt vmcnt(8) lgkmcnt(0)
	s_barrier
	v_mfma_f32_16x16x32_bf16 v[126:129], v[130:133], v[186:189], v[126:129]
	v_mfma_f32_16x16x32_bf16 v[122:125], v[152:155], v[186:189], v[122:125]
	v_mfma_f32_16x16x32_bf16 v[110:113], v[130:133], v[194:197], v[110:113]
	v_mfma_f32_16x16x32_bf16 v[106:109], v[152:155], v[194:197], v[106:109]
	v_mfma_f32_16x16x32_bf16 v[94:97], v[130:133], v[202:205], v[94:97]
	v_mfma_f32_16x16x32_bf16 v[90:93], v[152:155], v[202:205], v[90:93]
	v_mfma_f32_16x16x32_bf16 v[78:81], v[130:133], v[210:213], v[78:81]
	v_mfma_f32_16x16x32_bf16 v[74:77], v[152:155], v[210:213], v[74:77]
	v_mfma_f32_16x16x32_bf16 v[126:129], v[134:137], v[190:193], v[126:129]
	v_mfma_f32_16x16x32_bf16 v[122:125], v[156:159], v[190:193], v[122:125]
	v_mfma_f32_16x16x32_bf16 v[110:113], v[134:137], v[198:201], v[110:113]
	v_mfma_f32_16x16x32_bf16 v[106:109], v[156:159], v[198:201], v[106:109]
	v_mfma_f32_16x16x32_bf16 v[94:97], v[134:137], v[206:209], v[94:97]
	v_mfma_f32_16x16x32_bf16 v[90:93], v[156:159], v[206:209], v[90:93]
	v_mfma_f32_16x16x32_bf16 v[78:81], v[134:137], v[214:217], v[78:81]
	v_mfma_f32_16x16x32_bf16 v[74:77], v[156:159], v[214:217], v[74:77]
	v_mfma_f32_16x16x32_bf16 v[118:121], v[160:163], v[186:189], v[118:121]
	v_mfma_f32_16x16x32_bf16 v[114:117], v[178:181], v[186:189], v[114:117]
	v_mfma_f32_16x16x32_bf16 v[102:105], v[160:163], v[194:197], v[102:105]
	v_mfma_f32_16x16x32_bf16 v[98:101], v[178:181], v[194:197], v[98:101]
	v_mfma_f32_16x16x32_bf16 v[86:89], v[160:163], v[202:205], v[86:89]
	v_mfma_f32_16x16x32_bf16 v[82:85], v[178:181], v[202:205], v[82:85]
	v_mfma_f32_16x16x32_bf16 v[70:73], v[160:163], v[210:213], v[70:73]
	v_mfma_f32_16x16x32_bf16 v[66:69], v[178:181], v[210:213], v[66:69]
	v_mfma_f32_16x16x32_bf16 v[118:121], v[174:177], v[190:193], v[118:121]
	v_mfma_f32_16x16x32_bf16 v[114:117], v[182:185], v[190:193], v[114:117]
	v_mfma_f32_16x16x32_bf16 v[102:105], v[174:177], v[198:201], v[102:105]
	v_mfma_f32_16x16x32_bf16 v[98:101], v[182:185], v[198:201], v[98:101]
	v_mfma_f32_16x16x32_bf16 v[86:89], v[174:177], v[206:209], v[86:89]
	v_mfma_f32_16x16x32_bf16 v[82:85], v[182:185], v[206:209], v[82:85]
	v_mfma_f32_16x16x32_bf16 v[70:73], v[174:177], v[214:217], v[70:73]
	v_mfma_f32_16x16x32_bf16 v[66:69], v[182:185], v[214:217], v[66:69]
	s_barrier
	s_add_i32 s14, s18, s42
	s_mov_b32 m0, s14
	s_add_u32 vcc_lo, s10, 0x80
	s_addc_u32 vcc_hi, s11, 0
	global_load_lds_dwordx4 v142, vcc
	s_add_i32 m0, s14, 0x2000
	s_add_u32 s10, s10, 0x100080
	s_addc_u32 s11, s11, 0
	s_add_i32 s14, s19, s42
	global_load_lds_dwordx4 v138, vcc
	s_mov_b32 m0, s14
	ds_read_b128 v[186:189], v172 offset:49152
	global_load_lds_dwordx4 v142, s[10:11]
	s_add_i32 m0, s14, 0x2000
	ds_read_b128 v[190:193], v172 offset:50176
	global_load_lds_dwordx4 v138, s[10:11]
	s_mov_b32 m0, s73
	ds_read_b128 v[194:197], v172 offset:51200
	global_load_lds_dwordx4 v144, s[100:101]
	s_mov_b32 m0, s82
	ds_read_b128 v[198:201], v172 offset:52224
	global_load_lds_dwordx4 v140, s[100:101]
	ds_read_b128 v[214:217], v172 offset:56320
	ds_read_b128 v[210:213], v172 offset:55296
	ds_read_b128 v[206:209], v172 offset:54272
	ds_read_b128 v[202:205], v172 offset:53248
	s_waitcnt vmcnt(8) lgkmcnt(0)
	s_nop 0
	s_barrier
	v_mfma_f32_16x16x32_bf16 v[62:65], v[130:133], v[186:189], v[62:65]
	v_mfma_f32_16x16x32_bf16 v[58:61], v[152:155], v[186:189], v[58:61]
	v_mfma_f32_16x16x32_bf16 v[46:49], v[130:133], v[194:197], v[46:49]
	v_mfma_f32_16x16x32_bf16 v[42:45], v[152:155], v[194:197], v[42:45]
	v_mfma_f32_16x16x32_bf16 v[30:33], v[130:133], v[202:205], v[30:33]
	v_mfma_f32_16x16x32_bf16 v[26:29], v[152:155], v[202:205], v[26:29]
	v_mfma_f32_16x16x32_bf16 v[12:15], v[130:133], v[210:213], v[12:15]
	v_mfma_f32_16x16x32_bf16 v[8:11], v[152:155], v[210:213], v[8:11]
	v_mfma_f32_16x16x32_bf16 v[62:65], v[134:137], v[190:193], v[62:65]
	v_mfma_f32_16x16x32_bf16 v[58:61], v[156:159], v[190:193], v[58:61]
	v_mfma_f32_16x16x32_bf16 v[46:49], v[134:137], v[198:201], v[46:49]
	v_mfma_f32_16x16x32_bf16 v[42:45], v[156:159], v[198:201], v[42:45]
	v_mfma_f32_16x16x32_bf16 v[30:33], v[134:137], v[206:209], v[30:33]
	v_mfma_f32_16x16x32_bf16 v[26:29], v[156:159], v[206:209], v[26:29]
	v_mfma_f32_16x16x32_bf16 v[12:15], v[134:137], v[214:217], v[12:15]
	v_mfma_f32_16x16x32_bf16 v[8:11], v[156:159], v[214:217], v[8:11]
	v_mfma_f32_16x16x32_bf16 v[54:57], v[160:163], v[186:189], v[54:57]
	v_mfma_f32_16x16x32_bf16 v[50:53], v[178:181], v[186:189], v[50:53]
	v_mfma_f32_16x16x32_bf16 v[38:41], v[160:163], v[194:197], v[38:41]
	v_mfma_f32_16x16x32_bf16 v[34:37], v[178:181], v[194:197], v[34:37]
	v_mfma_f32_16x16x32_bf16 v[22:25], v[160:163], v[202:205], v[22:25]
	v_mfma_f32_16x16x32_bf16 v[18:21], v[178:181], v[202:205], v[18:21]
	v_mfma_f32_16x16x32_bf16 v[4:7], v[160:163], v[210:213], v[4:7]
	v_mfma_f32_16x16x32_bf16 v[0:3], v[178:181], v[210:213], v[0:3]
	v_mfma_f32_16x16x32_bf16 v[54:57], v[174:177], v[190:193], v[54:57]
	v_mfma_f32_16x16x32_bf16 v[50:53], v[182:185], v[190:193], v[50:53]
	v_mfma_f32_16x16x32_bf16 v[38:41], v[174:177], v[198:201], v[38:41]
	v_mfma_f32_16x16x32_bf16 v[34:37], v[182:185], v[198:201], v[34:37]
	v_mfma_f32_16x16x32_bf16 v[22:25], v[174:177], v[206:209], v[22:25]
	v_mfma_f32_16x16x32_bf16 v[18:21], v[182:185], v[206:209], v[18:21]
	v_mfma_f32_16x16x32_bf16 v[4:7], v[174:177], v[214:217], v[4:7]
	v_mfma_f32_16x16x32_bf16 v[0:3], v[182:185], v[214:217], v[0:3]
	s_barrier
	s_add_i32 s27, s27, 2
	s_add_u32 s8, s8, 0x100
	s_addc_u32 s9, s9, 0
	s_add_u32 s0, s0, 0x100
	s_addc_u32 s1, s1, 0
	s_cmp_gt_u32 s27, 61
	s_cbranch_scc0 .LBB0_129
	s_and_b64 vcc, exec, s[24:25]
	s_cbranch_vccz .LBB0_132
	s_barrier

; #define PG8_STAGEA(bufoff, gbase, voff) PG8_STAGE_X(bufoff, gbase, voff, AUXA)
; #define PG8_STAGEB(bufoff, gbase, voff) PG8_STAGE_X(bufoff, gbase, voff, AUXB)
; #define PG8_LDA(dst, b, h) do { _Pragma("unroll") for (int m = 0; m < 4; ++m) _Pragma("unroll") for (int k = 0; k < 2; ++k) dst[m][k] = *(const PG8_LAS bf16x8*)(lds + PG8_SA(b, h) + aoff + m * 2048 + k * 1024); } while (0)
; #define PG8_LDB(dst, b, h) do { _Pragma("unroll") for (int n = 0; n < 2; ++n) _Pragma("unroll") for (int k = 0; k < 2; ++k) dst[n][k] = *(const PG8_LAS bf16x8*)(lds + PG8_SB(b, h) + boff + n * 2048 + k * 1024); } while (0)
; #define PG8_MMA(ai, bj, At, Bt) do { if (GEMM_PRIO_MODE == 0) __builtin_amdgcn_s_setprio(1); PG8_MMA_LOOPS \
;         acc[ai][bj][m][n] = __builtin_amdgcn_mfma_f32_16x16x32_bf16(Bt[n][k], At[m][k], acc[ai][bj][m][n], 0, 0, 0); if (GEMM_PRIO_MODE == 0) __builtin_amdgcn_s_setprio(0); } while (0)
; #define PG8_WAIT_V(n) asm volatile("s_waitcnt vmcnt(" #n ")" ::: "memory")
; #define PG8_WAIT_VR(n, nr, flag) asm volatile("s_cmp_eq_u32 %0, 0\n\ts_cbranch_scc1 .Lpg8s%=\n\ts_waitcnt vmcnt(" #nr ")\n\ts_branch .Lpg8d%=\n.Lpg8s%=:\n\ts_waitcnt vmcnt(" #n ")\n.Lpg8d%=:" :: "s"(flag) : "memory", "scc")
; #define PG8_WAIT_L(n) asm volatile("s_waitcnt lgkmcnt(" #n ")" ::: "memory")
; #define PG8_BAR __builtin_amdgcn_s_barrier()
; #define PG8_SCHED __builtin_amdgcn_sched_barrier(0)
;     ...
;             PG8_LDB(B0, 0, 0); PG8_LDB(B1, 0, 1); PG8_SCHED; PG8_LDA(At, 0, 0); PG8_STAGEA(PG8_SA(1, 1), a1 + hstepA, voffA);
;     ...
;             const int relax = __builtin_amdgcn_readfirstlane((t == 0 && ui > 0) ? 1 : 0);
;             PG8_WAIT_VR(8, 24, relax); PG8_WAIT_L(0); PG8_BAR; PG8_MMA(0, 0, At, B0); PG8_MMA(0, 1, At, B1); PG8_BAR; PG8_SCHED;
;     ...
;             PG8_WAIT_V(8); PG8_WAIT_L(0); PG8_BAR; PG8_MMA(0, 0, At, B0); PG8_MMA(0, 1, At, B1); PG8_BAR; PG8_SCHED;
;     ...
;             PG8_LDA(At, 0, 1); PG8_STAGEB(PG8_SB(0, 0), b2, voffB); PG8_STAGEB(PG8_SB(0, 1), b2 + hstepB, voffB); PG8_STAGEA(PG8_SA(0, 0), a2, voffA);
;     ...
;             PG8_WAIT_VR(8, 24, relax); PG8_WAIT_L(0); PG8_BAR; PG8_MMA(1, 0, At, B0); PG8_MMA(1, 1, At, B1); PG8_BAR; PG8_SCHED;
;     ...
;             PG8_WAIT_V(8); PG8_WAIT_L(0); PG8_BAR; PG8_MMA(1, 0, At, B0); PG8_MMA(1, 1, At, B1); PG8_BAR; PG8_SCHED;
.LBB0_558:
	s_add_u32 s6, s38, 0xfff00080
	s_addc_u32 s7, s39, -1
	s_add_i32 s91, 0, 0x10000
	s_cmp_eq_u32 s90, 60
	s_cselect_b32 s41, s21, s7
	s_cselect_b32 s40, s82, s6
	s_cselect_b32 s17, s23, s1
	s_cselect_b32 s16, s83, s0
	s_add_i32 s94, 0, 0x14000
	s_add_i32 m0, s13, 0xc000
	ds_read_b128 v[130:133], v220
	global_load_lds_dwordx4 v144, s[38:39]
	s_add_i32 m0, s13, 0xe000
	ds_read_b128 v[134:137], v220 offset:1024
	global_load_lds_dwordx4 v146, s[38:39]
	ds_read_b128 v[148:151], v220 offset:2048
	ds_read_b128 v[152:155], v220 offset:3072
	ds_read_b128 v[162:165], v220 offset:16384
	ds_read_b128 v[166:169], v220 offset:17408
	ds_read_b128 v[170:173], v220 offset:18432
	ds_read_b128 v[174:177], v220 offset:19456
	ds_read_b128 v[178:181], v161
	ds_read_b128 v[182:185], v161 offset:1024
	ds_read_b128 v[186:189], v161 offset:2048
	ds_read_b128 v[190:193], v161 offset:3072
	ds_read_b128 v[194:197], v161 offset:4096
	ds_read_b128 v[198:201], v161 offset:5120
	ds_read_b128 v[202:205], v161 offset:6144
	ds_read_b128 v[206:209], v161 offset:7168
	s_waitcnt vmcnt(8) lgkmcnt(0)
	s_barrier
	v_mfma_f32_16x16x32_bf16 v[126:129], v[130:133], v[178:181], v[126:129]
	v_mfma_f32_16x16x32_bf16 v[122:125], v[148:151], v[178:181], v[122:125]
	v_mfma_f32_16x16x32_bf16 v[110:113], v[130:133], v[186:189], v[110:113]
	v_mfma_f32_16x16x32_bf16 v[106:109], v[148:151], v[186:189], v[106:109]
	v_mfma_f32_16x16x32_bf16 v[94:97], v[130:133], v[194:197], v[94:97]
	v_mfma_f32_16x16x32_bf16 v[90:93], v[148:151], v[194:197], v[90:93]
	v_mfma_f32_16x16x32_bf16 v[78:81], v[130:133], v[202:205], v[78:81]
	v_mfma_f32_16x16x32_bf16 v[74:77], v[148:151], v[202:205], v[74:77]
	v_mfma_f32_16x16x32_bf16 v[126:129], v[134:137], v[182:185], v[126:129]
	v_mfma_f32_16x16x32_bf16 v[122:125], v[152:155], v[182:185], v[122:125]
	v_mfma_f32_16x16x32_bf16 v[110:113], v[134:137], v[190:193], v[110:113]
	v_mfma_f32_16x16x32_bf16 v[106:109], v[152:155], v[190:193], v[106:109]
	v_mfma_f32_16x16x32_bf16 v[94:97], v[134:137], v[198:201], v[94:97]
	v_mfma_f32_16x16x32_bf16 v[90:93], v[152:155], v[198:201], v[90:93]
	v_mfma_f32_16x16x32_bf16 v[78:81], v[134:137], v[206:209], v[78:81]
	v_mfma_f32_16x16x32_bf16 v[74:77], v[152:155], v[206:209], v[74:77]
	v_mfma_f32_16x16x32_bf16 v[118:121], v[162:165], v[178:181], v[118:121]
	v_mfma_f32_16x16x32_bf16 v[114:117], v[170:173], v[178:181], v[114:117]
	v_mfma_f32_16x16x32_bf16 v[102:105], v[162:165], v[186:189], v[102:105]
	v_mfma_f32_16x16x32_bf16 v[98:101], v[170:173], v[186:189], v[98:101]
	v_mfma_f32_16x16x32_bf16 v[86:89], v[162:165], v[194:197], v[86:89]
	v_mfma_f32_16x16x32_bf16 v[82:85], v[170:173], v[194:197], v[82:85]
	v_mfma_f32_16x16x32_bf16 v[70:73], v[162:165], v[202:205], v[70:73]
	v_mfma_f32_16x16x32_bf16 v[66:69], v[170:173], v[202:205], v[66:69]
	v_mfma_f32_16x16x32_bf16 v[118:121], v[166:169], v[182:185], v[118:121]
	v_mfma_f32_16x16x32_bf16 v[114:117], v[174:177], v[182:185], v[114:117]
	v_mfma_f32_16x16x32_bf16 v[102:105], v[166:169], v[190:193], v[102:105]
	v_mfma_f32_16x16x32_bf16 v[98:101], v[174:177], v[190:193], v[98:101]
	v_mfma_f32_16x16x32_bf16 v[86:89], v[166:169], v[198:201], v[86:89]
	v_mfma_f32_16x16x32_bf16 v[82:85], v[174:177], v[198:201], v[82:85]
	v_mfma_f32_16x16x32_bf16 v[70:73], v[166:169], v[206:209], v[70:73]
	v_mfma_f32_16x16x32_bf16 v[66:69], v[174:177], v[206:209], v[66:69]
	s_barrier
	s_add_i32 s6, s91, s12
	s_mov_b32 m0, s6
	ds_read_b128 v[178:181], v161 offset:16384
	global_load_lds_dwordx4 v16, s[16:17]
	s_add_i32 m0, s6, 0x2000
	s_add_u32 s6, s16, 0x100000
	s_addc_u32 s7, s17, 0
	s_add_i32 s91, s94, s12
	global_load_lds_dwordx4 v138, s[16:17]
	s_mov_b32 m0, s91
	ds_read_b128 v[182:185], v161 offset:17408
	global_load_lds_dwordx4 v16, s[6:7]
	s_add_i32 m0, s91, 0x2000
	ds_read_b128 v[186:189], v161 offset:18432
	global_load_lds_dwordx4 v138, s[6:7]
	s_mov_b32 m0, s13
	ds_read_b128 v[190:193], v161 offset:19456
	global_load_lds_dwordx4 v142, s[40:41]
	s_mov_b32 m0, s42
	ds_read_b128 v[206:209], v161 offset:23552
	global_load_lds_dwordx4 v140, s[40:41]
	ds_read_b128 v[202:205], v161 offset:22528
	ds_read_b128 v[198:201], v161 offset:21504
	ds_read_b128 v[194:197], v161 offset:20480
	s_waitcnt vmcnt(8) lgkmcnt(0)
	s_barrier
	v_mfma_f32_16x16x32_bf16 v[62:65], v[130:133], v[178:181], v[62:65]
	v_mfma_f32_16x16x32_bf16 v[58:61], v[148:151], v[178:181], v[58:61]
	v_mfma_f32_16x16x32_bf16 v[46:49], v[130:133], v[186:189], v[46:49]
	v_mfma_f32_16x16x32_bf16 v[42:45], v[148:151], v[186:189], v[42:45]
	v_mfma_f32_16x16x32_bf16 v[30:33], v[130:133], v[194:197], v[30:33]
	v_mfma_f32_16x16x32_bf16 v[26:29], v[148:151], v[194:197], v[26:29]
	v_mfma_f32_16x16x32_bf16 v[12:15], v[130:133], v[202:205], v[12:15]
	v_mfma_f32_16x16x32_bf16 v[8:11], v[148:151], v[202:205], v[8:11]
	v_mfma_f32_16x16x32_bf16 v[62:65], v[134:137], v[182:185], v[62:65]
	v_mfma_f32_16x16x32_bf16 v[58:61], v[152:155], v[182:185], v[58:61]
	v_mfma_f32_16x16x32_bf16 v[46:49], v[134:137], v[190:193], v[46:49]
	v_mfma_f32_16x16x32_bf16 v[42:45], v[152:155], v[190:193], v[42:45]
	v_mfma_f32_16x16x32_bf16 v[30:33], v[134:137], v[198:201], v[30:33]
	v_mfma_f32_16x16x32_bf16 v[26:29], v[152:155], v[198:201], v[26:29]
	v_mfma_f32_16x16x32_bf16 v[12:15], v[134:137], v[206:209], v[12:15]
	v_mfma_f32_16x16x32_bf16 v[8:11], v[152:155], v[206:209], v[8:11]
	v_mfma_f32_16x16x32_bf16 v[54:57], v[162:165], v[178:181], v[54:57]
	v_mfma_f32_16x16x32_bf16 v[50:53], v[170:173], v[178:181], v[50:53]
	v_mfma_f32_16x16x32_bf16 v[38:41], v[162:165], v[186:189], v[38:41]
	v_mfma_f32_16x16x32_bf16 v[34:37], v[170:173], v[186:189], v[34:37]
	v_mfma_f32_16x16x32_bf16 v[22:25], v[162:165], v[194:197], v[22:25]
	v_mfma_f32_16x16x32_bf16 v[18:21], v[170:173], v[194:197], v[18:21]
	v_mfma_f32_16x16x32_bf16 v[4:7], v[162:165], v[202:205], v[4:7]
	v_mfma_f32_16x16x32_bf16 v[0:3], v[170:173], v[202:205], v[0:3]
	v_mfma_f32_16x16x32_bf16 v[54:57], v[166:169], v[182:185], v[54:57]
	v_mfma_f32_16x16x32_bf16 v[50:53], v[174:177], v[182:185], v[50:53]
	v_mfma_f32_16x16x32_bf16 v[38:41], v[166:169], v[190:193], v[38:41]
	v_mfma_f32_16x16x32_bf16 v[34:37], v[174:177], v[190:193], v[34:37]
	v_mfma_f32_16x16x32_bf16 v[22:25], v[166:169], v[198:201], v[22:25]
	v_mfma_f32_16x16x32_bf16 v[18:21], v[174:177], v[198:201], v[18:21]
	v_mfma_f32_16x16x32_bf16 v[4:7], v[166:169], v[206:209], v[4:7]
	v_mfma_f32_16x16x32_bf16 v[0:3], v[174:177], v[206:209], v[0:3]
	s_barrier
; #define PG8_STAGEA(bufoff, gbase, voff) PG8_STAGE_X(bufoff, gbase, voff, AUXA)
; #define PG8_STAGEB(bufoff, gbase, voff) PG8_STAGE_X(bufoff, gbase, voff, AUXB)
; #define PG8_LDA(dst, b, h) do { _Pragma("unroll") for (int m = 0; m < 4; ++m) _Pragma("unroll") for (int k = 0; k < 2; ++k) dst[m][k] = *(const PG8_LAS bf16x8*)(lds + PG8_SA(b, h) + aoff + m * 2048 + k * 1024); } while (0)
; #define PG8_LDB(dst, b, h) do { _Pragma("unroll") for (int n = 0; n < 2; ++n) _Pragma("unroll") for (int k = 0; k < 2; ++k) dst[n][k] = *(const PG8_LAS bf16x8*)(lds + PG8_SB(b, h) + boff + n * 2048 + k * 1024); } while (0)
; #define PG8_MMA(ai, bj, At, Bt) do { if (GEMM_PRIO_MODE == 0) __builtin_amdgcn_s_setprio(1); PG8_MMA_LOOPS \
;         acc[ai][bj][m][n] = __builtin_amdgcn_mfma_f32_16x16x32_bf16(Bt[n][k], At[m][k], acc[ai][bj][m][n], 0, 0, 0); if (GEMM_PRIO_MODE == 0) __builtin_amdgcn_s_setprio(0); } while (0)
; #define PG8_WAIT_V(n) asm volatile("s_waitcnt vmcnt(" #n ")" ::: "memory")
; #define PG8_WAIT_L(n) asm volatile("s_waitcnt lgkmcnt(" #n ")" ::: "memory")
; #define PG8_BAR __builtin_amdgcn_s_barrier()
; #define PG8_SCHED __builtin_amdgcn_sched_barrier(0)
;     ...
;             PG8_LDB(B0, 1, 0); PG8_LDB(B1, 1, 1); PG8_SCHED; PG8_LDA(At, 1, 0); PG8_STAGEA(PG8_SA(0, 1), a2 + hstepA, voffA);
;             PG8_WAIT_V(8); PG8_WAIT_L(0); PG8_BAR; PG8_MMA(0, 0, At, B0); PG8_MMA(0, 1, At, B1); PG8_BAR; PG8_SCHED;
;             PG8_LDA(At, 1, 1); PG8_STAGEB(PG8_SB(1, 0), b3, voffB); PG8_STAGEB(PG8_SB(1, 1), b3 + hstepB, voffB); PG8_STAGEA(PG8_SA(1, 0), a3, voffA);
;             PG8_WAIT_V(8); PG8_WAIT_L(0); PG8_BAR; PG8_MMA(1, 0, At, B0); PG8_MMA(1, 1, At, B1); PG8_BAR; PG8_SCHED;
	s_add_i32 s91, 0, 0x18000
	s_add_i32 s94, 0, 0x1c000
	s_add_u32 s6, s40, 0x100000
	s_addc_u32 s7, s41, 0
	s_mov_b32 m0, s43
	ds_read_b128 v[130:133], v220 offset:32768
	global_load_lds_dwordx4 v142, s[6:7]
	s_mov_b32 m0, s50
	ds_read_b128 v[134:137], v220 offset:33792
	global_load_lds_dwordx4 v140, s[6:7]
	ds_read_b128 v[148:151], v220 offset:34816
	ds_read_b128 v[152:155], v220 offset:35840
	ds_read_b128 v[162:165], v220 offset:49152
	ds_read_b128 v[166:169], v220 offset:50176
	ds_read_b128 v[170:173], v220 offset:51200
	ds_read_b128 v[174:177], v220 offset:52224
	ds_read_b128 v[178:181], v161 offset:32768
	ds_read_b128 v[182:185], v161 offset:33792
	ds_read_b128 v[186:189], v161 offset:34816
	ds_read_b128 v[190:193], v161 offset:35840
	ds_read_b128 v[194:197], v161 offset:36864
	ds_read_b128 v[198:201], v161 offset:37888
	ds_read_b128 v[202:205], v161 offset:38912
	ds_read_b128 v[206:209], v161 offset:39936
	s_waitcnt vmcnt(8) lgkmcnt(0)
	s_barrier
	v_mfma_f32_16x16x32_bf16 v[126:129], v[130:133], v[178:181], v[126:129]
	v_mfma_f32_16x16x32_bf16 v[122:125], v[148:151], v[178:181], v[122:125]
	v_mfma_f32_16x16x32_bf16 v[110:113], v[130:133], v[186:189], v[110:113]
	v_mfma_f32_16x16x32_bf16 v[106:109], v[148:151], v[186:189], v[106:109]
	v_mfma_f32_16x16x32_bf16 v[94:97], v[130:133], v[194:197], v[94:97]
	v_mfma_f32_16x16x32_bf16 v[90:93], v[148:151], v[194:197], v[90:93]
	v_mfma_f32_16x16x32_bf16 v[78:81], v[130:133], v[202:205], v[78:81]
	v_mfma_f32_16x16x32_bf16 v[74:77], v[148:151], v[202:205], v[74:77]
	v_mfma_f32_16x16x32_bf16 v[126:129], v[134:137], v[182:185], v[126:129]
	v_mfma_f32_16x16x32_bf16 v[122:125], v[152:155], v[182:185], v[122:125]
	v_mfma_f32_16x16x32_bf16 v[110:113], v[134:137], v[190:193], v[110:113]
	v_mfma_f32_16x16x32_bf16 v[106:109], v[152:155], v[190:193], v[106:109]
	v_mfma_f32_16x16x32_bf16 v[94:97], v[134:137], v[198:201], v[94:97]
	v_mfma_f32_16x16x32_bf16 v[90:93], v[152:155], v[198:201], v[90:93]
	v_mfma_f32_16x16x32_bf16 v[78:81], v[134:137], v[206:209], v[78:81]
	v_mfma_f32_16x16x32_bf16 v[74:77], v[152:155], v[206:209], v[74:77]
	v_mfma_f32_16x16x32_bf16 v[118:121], v[162:165], v[178:181], v[118:121]
	v_mfma_f32_16x16x32_bf16 v[114:117], v[170:173], v[178:181], v[114:117]
	v_mfma_f32_16x16x32_bf16 v[102:105], v[162:165], v[186:189], v[102:105]
	v_mfma_f32_16x16x32_bf16 v[98:101], v[170:173], v[186:189], v[98:101]
	v_mfma_f32_16x16x32_bf16 v[86:89], v[162:165], v[194:197], v[86:89]
	v_mfma_f32_16x16x32_bf16 v[82:85], v[170:173], v[194:197], v[82:85]
	v_mfma_f32_16x16x32_bf16 v[70:73], v[162:165], v[202:205], v[70:73]
	v_mfma_f32_16x16x32_bf16 v[66:69], v[170:173], v[202:205], v[66:69]
	v_mfma_f32_16x16x32_bf16 v[118:121], v[166:169], v[182:185], v[118:121]
	v_mfma_f32_16x16x32_bf16 v[114:117], v[174:177], v[182:185], v[114:117]
	v_mfma_f32_16x16x32_bf16 v[102:105], v[166:169], v[190:193], v[102:105]
	v_mfma_f32_16x16x32_bf16 v[98:101], v[174:177], v[190:193], v[98:101]
	v_mfma_f32_16x16x32_bf16 v[86:89], v[166:169], v[198:201], v[86:89]
	v_mfma_f32_16x16x32_bf16 v[82:85], v[174:177], v[198:201], v[82:85]
	v_mfma_f32_16x16x32_bf16 v[70:73], v[166:169], v[206:209], v[70:73]
	v_mfma_f32_16x16x32_bf16 v[66:69], v[174:177], v[206:209], v[66:69]
	s_barrier
	s_add_i32 s6, s91, s12
	s_mov_b32 m0, s6
	s_add_u32 s100, s16, 0x80
	s_addc_u32 s101, s17, 0
	global_load_lds_dwordx4 v16, s[100:101]
	s_add_i32 m0, s6, 0x2000
	s_add_u32 s6, s16, 0x100080
	s_addc_u32 s7, s17, 0
	s_add_i32 s16, s94, s12
	global_load_lds_dwordx4 v138, s[100:101]
	s_mov_b32 m0, s16
	ds_read_b128 v[178:181], v161 offset:49152
	global_load_lds_dwordx4 v16, s[6:7]
	s_add_i32 m0, s16, 0x2000
	ds_read_b128 v[182:185], v161 offset:50176
	global_load_lds_dwordx4 v138, s[6:7]
	s_mov_b32 m0, s68
	s_nop 0
	s_add_u32 vcc_lo, s40, 0x80
	s_addc_u32 vcc_hi, s41, 0
	global_load_lds_dwordx4 v142, vcc
	s_mov_b32 m0, s69
	ds_read_b128 v[186:189], v161 offset:51200
	global_load_lds_dwordx4 v140, vcc
	ds_read_b128 v[190:193], v161 offset:52224
	ds_read_b128 v[194:197], v161 offset:53248
	ds_read_b128 v[206:209], v161 offset:56320
	ds_read_b128 v[202:205], v161 offset:55296
	ds_read_b128 v[198:201], v161 offset:54272
	s_waitcnt vmcnt(8) lgkmcnt(0)
	s_nop 0
	s_barrier
	v_mfma_f32_16x16x32_bf16 v[62:65], v[130:133], v[178:181], v[62:65]
	v_mfma_f32_16x16x32_bf16 v[58:61], v[148:151], v[178:181], v[58:61]
	v_mfma_f32_16x16x32_bf16 v[46:49], v[130:133], v[186:189], v[46:49]
	v_mfma_f32_16x16x32_bf16 v[42:45], v[148:151], v[186:189], v[42:45]
	v_mfma_f32_16x16x32_bf16 v[30:33], v[130:133], v[194:197], v[30:33]
	v_mfma_f32_16x16x32_bf16 v[26:29], v[148:151], v[194:197], v[26:29]
	v_mfma_f32_16x16x32_bf16 v[12:15], v[130:133], v[202:205], v[12:15]
	v_mfma_f32_16x16x32_bf16 v[8:11], v[148:151], v[202:205], v[8:11]
	v_mfma_f32_16x16x32_bf16 v[62:65], v[134:137], v[182:185], v[62:65]
	v_mfma_f32_16x16x32_bf16 v[58:61], v[152:155], v[182:185], v[58:61]
	v_mfma_f32_16x16x32_bf16 v[46:49], v[134:137], v[190:193], v[46:49]
	v_mfma_f32_16x16x32_bf16 v[42:45], v[152:155], v[190:193], v[42:45]
	v_mfma_f32_16x16x32_bf16 v[30:33], v[134:137], v[198:201], v[30:33]
	v_mfma_f32_16x16x32_bf16 v[26:29], v[152:155], v[198:201], v[26:29]
	v_mfma_f32_16x16x32_bf16 v[12:15], v[134:137], v[206:209], v[12:15]
	v_mfma_f32_16x16x32_bf16 v[8:11], v[152:155], v[206:209], v[8:11]
	v_mfma_f32_16x16x32_bf16 v[54:57], v[162:165], v[178:181], v[54:57]
	v_mfma_f32_16x16x32_bf16 v[50:53], v[170:173], v[178:181], v[50:53]
	v_mfma_f32_16x16x32_bf16 v[38:41], v[162:165], v[186:189], v[38:41]
	v_mfma_f32_16x16x32_bf16 v[34:37], v[170:173], v[186:189], v[34:37]
	v_mfma_f32_16x16x32_bf16 v[22:25], v[162:165], v[194:197], v[22:25]
	v_mfma_f32_16x16x32_bf16 v[18:21], v[170:173], v[194:197], v[18:21]
	v_mfma_f32_16x16x32_bf16 v[4:7], v[162:165], v[202:205], v[4:7]
	v_mfma_f32_16x16x32_bf16 v[0:3], v[170:173], v[202:205], v[0:3]
	v_mfma_f32_16x16x32_bf16 v[54:57], v[166:169], v[182:185], v[54:57]
	v_mfma_f32_16x16x32_bf16 v[50:53], v[174:177], v[182:185], v[50:53]
	v_mfma_f32_16x16x32_bf16 v[38:41], v[166:169], v[190:193], v[38:41]
	v_mfma_f32_16x16x32_bf16 v[34:37], v[174:177], v[190:193], v[34:37]
	v_mfma_f32_16x16x32_bf16 v[22:25], v[166:169], v[198:201], v[22:25]
	v_mfma_f32_16x16x32_bf16 v[18:21], v[174:177], v[198:201], v[18:21]
	v_mfma_f32_16x16x32_bf16 v[4:7], v[166:169], v[206:209], v[4:7]
	v_mfma_f32_16x16x32_bf16 v[0:3], v[174:177], v[206:209], v[0:3]
	s_barrier
	s_add_i32 s90, s90, 2
	s_add_u32 s38, s38, 0x100
	s_addc_u32 s39, s39, 0
	s_add_u32 s0, s0, 0x100
	s_addc_u32 s1, s1, 0
	s_cmp_gt_u32 s90, 61
	s_cbranch_scc0 .LBB0_558
	s_and_b64 vcc, exec, s[18:19]
	s_cbranch_vccz .LBB0_561
	s_barrier

; #define PG8_STAGEA(bufoff, gbase, voff) PG8_STAGE_X(bufoff, gbase, voff, AUXA)
; #define PG8_STAGEB(bufoff, gbase, voff) PG8_STAGE_X(bufoff, gbase, voff, AUXB)
; #define PG8_LDA(dst, b, h) do { _Pragma("unroll") for (int m = 0; m < 4; ++m) _Pragma("unroll") for (int k = 0; k < 2; ++k) dst[m][k] = *(const PG8_LAS bf16x8*)(lds + PG8_SA(b, h) + aoff + m * 2048 + k * 1024); } while (0)
; #define PG8_LDB(dst, b, h) do { _Pragma("unroll") for (int n = 0; n < 2; ++n) _Pragma("unroll") for (int k = 0; k < 2; ++k) dst[n][k] = *(const PG8_LAS bf16x8*)(lds + PG8_SB(b, h) + boff + n * 2048 + k * 1024); } while (0)
; #define PG8_MMA(ai, bj, At, Bt) do { if (GEMM_PRIO_MODE == 0) __builtin_amdgcn_s_setprio(1); PG8_MMA_LOOPS \
;         acc[ai][bj][m][n] = __builtin_amdgcn_mfma_f32_16x16x32_bf16(Bt[n][k], At[m][k], acc[ai][bj][m][n], 0, 0, 0); if (GEMM_PRIO_MODE == 0) __builtin_amdgcn_s_setprio(0); } while (0)
; #define PG8_WAIT_V(n) asm volatile("s_waitcnt vmcnt(" #n ")" ::: "memory")
; #define PG8_WAIT_VR(n, nr, flag) asm volatile("s_cmp_eq_u32 %0, 0\n\ts_cbranch_scc1 .Lpg8s%=\n\ts_waitcnt vmcnt(" #nr ")\n\ts_branch .Lpg8d%=\n.Lpg8s%=:\n\ts_waitcnt vmcnt(" #n ")\n.Lpg8d%=:" :: "s"(flag) : "memory", "scc")
; #define PG8_WAIT_L(n) asm volatile("s_waitcnt lgkmcnt(" #n ")" ::: "memory")
; #define PG8_BAR __builtin_amdgcn_s_barrier()
; #define PG8_SCHED __builtin_amdgcn_sched_barrier(0)
;     ...
;             PG8_LDB(B0, 0, 0); PG8_LDB(B1, 0, 1); PG8_SCHED; PG8_LDA(At, 0, 0); PG8_STAGEA(PG8_SA(1, 1), a1 + hstepA, voffA);
;     ...
;             const int relax = __builtin_amdgcn_readfirstlane((t == 0 && ui > 0) ? 1 : 0);
;             PG8_WAIT_VR(8, 24, relax); PG8_WAIT_L(0); PG8_BAR; PG8_MMA(0, 0, At, B0); PG8_MMA(0, 1, At, B1); PG8_BAR; PG8_SCHED;
;     ...
;             PG8_WAIT_V(8); PG8_WAIT_L(0); PG8_BAR; PG8_MMA(0, 0, At, B0); PG8_MMA(0, 1, At, B1); PG8_BAR; PG8_SCHED;
;     ...
;             PG8_LDA(At, 0, 1); PG8_STAGEB(PG8_SB(0, 0), b2, voffB); PG8_STAGEB(PG8_SB(0, 1), b2 + hstepB, voffB); PG8_STAGEA(PG8_SA(0, 0), a2, voffA);
;     ...
;             PG8_WAIT_VR(8, 24, relax); PG8_WAIT_L(0); PG8_BAR; PG8_MMA(1, 0, At, B0); PG8_MMA(1, 1, At, B1); PG8_BAR; PG8_SCHED;
;     ...
;             PG8_WAIT_V(8); PG8_WAIT_L(0); PG8_BAR; PG8_MMA(1, 0, At, B0); PG8_MMA(1, 1, At, B1); PG8_BAR; PG8_SCHED;
.LBB0_712:
	s_add_u32 s6, s40, 0xfff00080
	s_addc_u32 s7, s41, -1
	s_add_i32 s95, 0, 0x10000
	s_cmp_eq_u32 s39, 60
	s_cselect_b32 s43, s0, s7
	s_cselect_b32 s42, s1, s6
	s_cselect_b32 s17, s23, s13
	s_cselect_b32 s16, s25, s12
	s_add_i32 vcc_lo, 0, 0x14000
	s_add_i32 m0, s69, 0xc000
	ds_read_b128 v[150:153], v222
	global_load_lds_dwordx4 v140, s[40:41]
	s_add_i32 m0, s69, 0xe000
	ds_read_b128 v[154:157], v222 offset:1024
	global_load_lds_dwordx4 v142, s[40:41]
	ds_read_b128 v[158:161], v222 offset:2048
	ds_read_b128 v[162:165], v222 offset:3072
	ds_read_b128 v[166:169], v222 offset:16384
	ds_read_b128 v[170:173], v222 offset:17408
	ds_read_b128 v[174:177], v222 offset:18432
	ds_read_b128 v[178:181], v222 offset:19456
	ds_read_b128 v[182:185], v148
	ds_read_b128 v[186:189], v148 offset:1024
	ds_read_b128 v[190:193], v148 offset:2048
	ds_read_b128 v[194:197], v148 offset:3072
	ds_read_b128 v[198:201], v148 offset:4096
	ds_read_b128 v[202:205], v148 offset:5120
	ds_read_b128 v[206:209], v148 offset:6144
	ds_read_b128 v[210:213], v148 offset:7168
	s_waitcnt vmcnt(8) lgkmcnt(0)
	s_barrier
	v_mfma_f32_16x16x32_bf16 v[126:129], v[150:153], v[182:185], v[126:129]
	v_mfma_f32_16x16x32_bf16 v[122:125], v[158:161], v[182:185], v[122:125]
	v_mfma_f32_16x16x32_bf16 v[110:113], v[150:153], v[190:193], v[110:113]
	v_mfma_f32_16x16x32_bf16 v[106:109], v[158:161], v[190:193], v[106:109]
	v_mfma_f32_16x16x32_bf16 v[94:97], v[150:153], v[198:201], v[94:97]
	v_mfma_f32_16x16x32_bf16 v[90:93], v[158:161], v[198:201], v[90:93]
	v_mfma_f32_16x16x32_bf16 v[78:81], v[150:153], v[206:209], v[78:81]
	v_mfma_f32_16x16x32_bf16 v[74:77], v[158:161], v[206:209], v[74:77]
	v_mfma_f32_16x16x32_bf16 v[126:129], v[154:157], v[186:189], v[126:129]
	v_mfma_f32_16x16x32_bf16 v[122:125], v[162:165], v[186:189], v[122:125]
	v_mfma_f32_16x16x32_bf16 v[110:113], v[154:157], v[194:197], v[110:113]
	v_mfma_f32_16x16x32_bf16 v[106:109], v[162:165], v[194:197], v[106:109]
	v_mfma_f32_16x16x32_bf16 v[94:97], v[154:157], v[202:205], v[94:97]
	v_mfma_f32_16x16x32_bf16 v[90:93], v[162:165], v[202:205], v[90:93]
	v_mfma_f32_16x16x32_bf16 v[78:81], v[154:157], v[210:213], v[78:81]
	v_mfma_f32_16x16x32_bf16 v[74:77], v[162:165], v[210:213], v[74:77]
	v_mfma_f32_16x16x32_bf16 v[118:121], v[166:169], v[182:185], v[118:121]
	v_mfma_f32_16x16x32_bf16 v[114:117], v[174:177], v[182:185], v[114:117]
	v_mfma_f32_16x16x32_bf16 v[102:105], v[166:169], v[190:193], v[102:105]
	v_mfma_f32_16x16x32_bf16 v[98:101], v[174:177], v[190:193], v[98:101]
	v_mfma_f32_16x16x32_bf16 v[86:89], v[166:169], v[198:201], v[86:89]
	v_mfma_f32_16x16x32_bf16 v[82:85], v[174:177], v[198:201], v[82:85]
	v_mfma_f32_16x16x32_bf16 v[70:73], v[166:169], v[206:209], v[70:73]
	v_mfma_f32_16x16x32_bf16 v[66:69], v[174:177], v[206:209], v[66:69]
	v_mfma_f32_16x16x32_bf16 v[118:121], v[170:173], v[186:189], v[118:121]
	v_mfma_f32_16x16x32_bf16 v[114:117], v[178:181], v[186:189], v[114:117]
	v_mfma_f32_16x16x32_bf16 v[102:105], v[170:173], v[194:197], v[102:105]
	v_mfma_f32_16x16x32_bf16 v[98:101], v[178:181], v[194:197], v[98:101]
	v_mfma_f32_16x16x32_bf16 v[86:89], v[170:173], v[202:205], v[86:89]
	v_mfma_f32_16x16x32_bf16 v[82:85], v[178:181], v[202:205], v[82:85]
	v_mfma_f32_16x16x32_bf16 v[70:73], v[170:173], v[210:213], v[70:73]
	v_mfma_f32_16x16x32_bf16 v[66:69], v[178:181], v[210:213], v[66:69]
	s_barrier
	s_add_i32 s6, s95, s50
	s_mov_b32 m0, s6
	ds_read_b128 v[182:185], v148 offset:16384
	global_load_lds_dwordx4 v134, s[16:17]
	s_add_i32 m0, s6, 0x2000
	s_add_u32 s6, s16, 0x100000
	s_addc_u32 s7, s17, 0
	s_add_i32 s95, vcc_lo, s50
	global_load_lds_dwordx4 v130, s[16:17]
	s_mov_b32 m0, s95
	ds_read_b128 v[186:189], v148 offset:17408
	global_load_lds_dwordx4 v134, s[6:7]
	s_add_i32 m0, s95, 0x2000
	ds_read_b128 v[190:193], v148 offset:18432
	global_load_lds_dwordx4 v130, s[6:7]
	s_mov_b32 m0, s69
	ds_read_b128 v[194:197], v148 offset:19456
	global_load_lds_dwordx4 v136, s[42:43]
	s_mov_b32 m0, s72
	ds_read_b128 v[210:213], v148 offset:23552
	global_load_lds_dwordx4 v132, s[42:43]
	ds_read_b128 v[206:209], v148 offset:22528
	ds_read_b128 v[202:205], v148 offset:21504
	ds_read_b128 v[198:201], v148 offset:20480
	s_waitcnt vmcnt(8) lgkmcnt(0)
	s_barrier
	v_mfma_f32_16x16x32_bf16 v[62:65], v[150:153], v[182:185], v[62:65]
	v_mfma_f32_16x16x32_bf16 v[58:61], v[158:161], v[182:185], v[58:61]
	v_mfma_f32_16x16x32_bf16 v[46:49], v[150:153], v[190:193], v[46:49]
	v_mfma_f32_16x16x32_bf16 v[42:45], v[158:161], v[190:193], v[42:45]
	v_mfma_f32_16x16x32_bf16 v[30:33], v[150:153], v[198:201], v[30:33]
	v_mfma_f32_16x16x32_bf16 v[26:29], v[158:161], v[198:201], v[26:29]
	v_mfma_f32_16x16x32_bf16 v[12:15], v[150:153], v[206:209], v[12:15]
	v_mfma_f32_16x16x32_bf16 v[8:11], v[158:161], v[206:209], v[8:11]
	v_mfma_f32_16x16x32_bf16 v[62:65], v[154:157], v[186:189], v[62:65]
	v_mfma_f32_16x16x32_bf16 v[58:61], v[162:165], v[186:189], v[58:61]
	v_mfma_f32_16x16x32_bf16 v[46:49], v[154:157], v[194:197], v[46:49]
	v_mfma_f32_16x16x32_bf16 v[42:45], v[162:165], v[194:197], v[42:45]
	v_mfma_f32_16x16x32_bf16 v[30:33], v[154:157], v[202:205], v[30:33]
	v_mfma_f32_16x16x32_bf16 v[26:29], v[162:165], v[202:205], v[26:29]
	v_mfma_f32_16x16x32_bf16 v[12:15], v[154:157], v[210:213], v[12:15]
	v_mfma_f32_16x16x32_bf16 v[8:11], v[162:165], v[210:213], v[8:11]
	v_mfma_f32_16x16x32_bf16 v[54:57], v[166:169], v[182:185], v[54:57]
	v_mfma_f32_16x16x32_bf16 v[50:53], v[174:177], v[182:185], v[50:53]
	v_mfma_f32_16x16x32_bf16 v[38:41], v[166:169], v[190:193], v[38:41]
	v_mfma_f32_16x16x32_bf16 v[34:37], v[174:177], v[190:193], v[34:37]
	v_mfma_f32_16x16x32_bf16 v[22:25], v[166:169], v[198:201], v[22:25]
	v_mfma_f32_16x16x32_bf16 v[18:21], v[174:177], v[198:201], v[18:21]
	v_mfma_f32_16x16x32_bf16 v[4:7], v[166:169], v[206:209], v[4:7]
	v_mfma_f32_16x16x32_bf16 v[0:3], v[174:177], v[206:209], v[0:3]
	v_mfma_f32_16x16x32_bf16 v[54:57], v[170:173], v[186:189], v[54:57]
	v_mfma_f32_16x16x32_bf16 v[50:53], v[178:181], v[186:189], v[50:53]
	v_mfma_f32_16x16x32_bf16 v[38:41], v[170:173], v[194:197], v[38:41]
	v_mfma_f32_16x16x32_bf16 v[34:37], v[178:181], v[194:197], v[34:37]
	v_mfma_f32_16x16x32_bf16 v[22:25], v[170:173], v[202:205], v[22:25]
	v_mfma_f32_16x16x32_bf16 v[18:21], v[178:181], v[202:205], v[18:21]
	v_mfma_f32_16x16x32_bf16 v[4:7], v[170:173], v[210:213], v[4:7]
	v_mfma_f32_16x16x32_bf16 v[0:3], v[178:181], v[210:213], v[0:3]
	s_barrier
; #define PG8_STAGEA(bufoff, gbase, voff) PG8_STAGE_X(bufoff, gbase, voff, AUXA)
; #define PG8_STAGEB(bufoff, gbase, voff) PG8_STAGE_X(bufoff, gbase, voff, AUXB)
; #define PG8_LDA(dst, b, h) do { _Pragma("unroll") for (int m = 0; m < 4; ++m) _Pragma("unroll") for (int k = 0; k < 2; ++k) dst[m][k] = *(const PG8_LAS bf16x8*)(lds + PG8_SA(b, h) + aoff + m * 2048 + k * 1024); } while (0)
; #define PG8_LDB(dst, b, h) do { _Pragma("unroll") for (int n = 0; n < 2; ++n) _Pragma("unroll") for (int k = 0; k < 2; ++k) dst[n][k] = *(const PG8_LAS bf16x8*)(lds + PG8_SB(b, h) + boff + n * 2048 + k * 1024); } while (0)
; #define PG8_MMA(ai, bj, At, Bt) do { if (GEMM_PRIO_MODE == 0) __builtin_amdgcn_s_setprio(1); PG8_MMA_LOOPS \
;         acc[ai][bj][m][n] = __builtin_amdgcn_mfma_f32_16x16x32_bf16(Bt[n][k], At[m][k], acc[ai][bj][m][n], 0, 0, 0); if (GEMM_PRIO_MODE == 0) __builtin_amdgcn_s_setprio(0); } while (0)
; #define PG8_WAIT_V(n) asm volatile("s_waitcnt vmcnt(" #n ")" ::: "memory")
; #define PG8_WAIT_L(n) asm volatile("s_waitcnt lgkmcnt(" #n ")" ::: "memory")
; #define PG8_BAR __builtin_amdgcn_s_barrier()
; #define PG8_SCHED __builtin_amdgcn_sched_barrier(0)
;     ...
;             PG8_LDB(B0, 1, 0); PG8_LDB(B1, 1, 1); PG8_SCHED; PG8_LDA(At, 1, 0); PG8_STAGEA(PG8_SA(0, 1), a2 + hstepA, voffA);
;             PG8_WAIT_V(8); PG8_WAIT_L(0); PG8_BAR; PG8_MMA(0, 0, At, B0); PG8_MMA(0, 1, At, B1); PG8_BAR; PG8_SCHED;
;             PG8_LDA(At, 1, 1); PG8_STAGEB(PG8_SB(1, 0), b3, voffB); PG8_STAGEB(PG8_SB(1, 1), b3 + hstepB, voffB); PG8_STAGEA(PG8_SA(1, 0), a3, voffA);
;             PG8_WAIT_V(8); PG8_WAIT_L(0); PG8_BAR; PG8_MMA(1, 0, At, B0); PG8_MMA(1, 1, At, B1); PG8_BAR; PG8_SCHED;
	s_add_i32 s95, 0, 0x18000
	s_add_i32 vcc_lo, 0, 0x1c000
	s_add_u32 s6, s42, 0x100000
	s_addc_u32 s7, s43, 0
	s_mov_b32 m0, s73
	ds_read_b128 v[150:153], v222 offset:32768
	global_load_lds_dwordx4 v136, s[6:7]
	s_mov_b32 m0, s82
	ds_read_b128 v[154:157], v222 offset:33792
	global_load_lds_dwordx4 v132, s[6:7]
	ds_read_b128 v[158:161], v222 offset:34816
	ds_read_b128 v[162:165], v222 offset:35840
	ds_read_b128 v[166:169], v222 offset:49152
	ds_read_b128 v[170:173], v222 offset:50176
	ds_read_b128 v[174:177], v222 offset:51200
	ds_read_b128 v[178:181], v222 offset:52224
	ds_read_b128 v[182:185], v148 offset:32768
	ds_read_b128 v[186:189], v148 offset:33792
	ds_read_b128 v[190:193], v148 offset:34816
	ds_read_b128 v[194:197], v148 offset:35840
	ds_read_b128 v[198:201], v148 offset:36864
	ds_read_b128 v[202:205], v148 offset:37888
	ds_read_b128 v[206:209], v148 offset:38912
	ds_read_b128 v[210:213], v148 offset:39936
	s_waitcnt vmcnt(8) lgkmcnt(0)
	s_barrier
	v_mfma_f32_16x16x32_bf16 v[126:129], v[150:153], v[182:185], v[126:129]
	v_mfma_f32_16x16x32_bf16 v[122:125], v[158:161], v[182:185], v[122:125]
	v_mfma_f32_16x16x32_bf16 v[110:113], v[150:153], v[190:193], v[110:113]
	v_mfma_f32_16x16x32_bf16 v[106:109], v[158:161], v[190:193], v[106:109]
	v_mfma_f32_16x16x32_bf16 v[94:97], v[150:153], v[198:201], v[94:97]
	v_mfma_f32_16x16x32_bf16 v[90:93], v[158:161], v[198:201], v[90:93]
	v_mfma_f32_16x16x32_bf16 v[78:81], v[150:153], v[206:209], v[78:81]
	v_mfma_f32_16x16x32_bf16 v[74:77], v[158:161], v[206:209], v[74:77]
	v_mfma_f32_16x16x32_bf16 v[126:129], v[154:157], v[186:189], v[126:129]
	v_mfma_f32_16x16x32_bf16 v[122:125], v[162:165], v[186:189], v[122:125]
	v_mfma_f32_16x16x32_bf16 v[110:113], v[154:157], v[194:197], v[110:113]
	v_mfma_f32_16x16x32_bf16 v[106:109], v[162:165], v[194:197], v[106:109]
	v_mfma_f32_16x16x32_bf16 v[94:97], v[154:157], v[202:205], v[94:97]
	v_mfma_f32_16x16x32_bf16 v[90:93], v[162:165], v[202:205], v[90:93]
	v_mfma_f32_16x16x32_bf16 v[78:81], v[154:157], v[210:213], v[78:81]
	v_mfma_f32_16x16x32_bf16 v[74:77], v[162:165], v[210:213], v[74:77]
	v_mfma_f32_16x16x32_bf16 v[118:121], v[166:169], v[182:185], v[118:121]
	v_mfma_f32_16x16x32_bf16 v[114:117], v[174:177], v[182:185], v[114:117]
	v_mfma_f32_16x16x32_bf16 v[102:105], v[166:169], v[190:193], v[102:105]
	v_mfma_f32_16x16x32_bf16 v[98:101], v[174:177], v[190:193], v[98:101]
	v_mfma_f32_16x16x32_bf16 v[86:89], v[166:169], v[198:201], v[86:89]
	v_mfma_f32_16x16x32_bf16 v[82:85], v[174:177], v[198:201], v[82:85]
	v_mfma_f32_16x16x32_bf16 v[70:73], v[166:169], v[206:209], v[70:73]
	v_mfma_f32_16x16x32_bf16 v[66:69], v[174:177], v[206:209], v[66:69]
	v_mfma_f32_16x16x32_bf16 v[118:121], v[170:173], v[186:189], v[118:121]
	v_mfma_f32_16x16x32_bf16 v[114:117], v[178:181], v[186:189], v[114:117]
	v_mfma_f32_16x16x32_bf16 v[102:105], v[170:173], v[194:197], v[102:105]
	v_mfma_f32_16x16x32_bf16 v[98:101], v[178:181], v[194:197], v[98:101]
	v_mfma_f32_16x16x32_bf16 v[86:89], v[170:173], v[202:205], v[86:89]
	v_mfma_f32_16x16x32_bf16 v[82:85], v[178:181], v[202:205], v[82:85]
	v_mfma_f32_16x16x32_bf16 v[70:73], v[170:173], v[210:213], v[70:73]
	v_mfma_f32_16x16x32_bf16 v[66:69], v[178:181], v[210:213], v[66:69]
	s_barrier
	s_add_i32 s6, s95, s50
	s_mov_b32 m0, s6
	s_add_u32 s100, s16, 0x80
	s_addc_u32 s101, s17, 0
	global_load_lds_dwordx4 v134, s[100:101]
	s_add_i32 m0, s6, 0x2000
	s_add_u32 s6, s16, 0x100080
	s_addc_u32 s7, s17, 0
	s_add_i32 s16, vcc_lo, s50
	global_load_lds_dwordx4 v130, s[100:101]
	s_mov_b32 m0, s16
	ds_read_b128 v[182:185], v148 offset:49152
	global_load_lds_dwordx4 v134, s[6:7]
	s_add_i32 m0, s16, 0x2000
	ds_read_b128 v[186:189], v148 offset:50176
	global_load_lds_dwordx4 v130, s[6:7]
	s_mov_b32 m0, s83
	s_nop 0
	s_add_u32 s100, s42, 0x80
	s_addc_u32 s101, s43, 0
	global_load_lds_dwordx4 v136, s[100:101]
	s_mov_b32 m0, s90
	ds_read_b128 v[190:193], v148 offset:51200
	global_load_lds_dwordx4 v132, s[100:101]
	ds_read_b128 v[194:197], v148 offset:52224
	ds_read_b128 v[198:201], v148 offset:53248
	ds_read_b128 v[210:213], v148 offset:56320
	ds_read_b128 v[206:209], v148 offset:55296
	ds_read_b128 v[202:205], v148 offset:54272
	s_waitcnt vmcnt(8) lgkmcnt(0)
	s_nop 0
	s_barrier
	v_mfma_f32_16x16x32_bf16 v[62:65], v[150:153], v[182:185], v[62:65]
	v_mfma_f32_16x16x32_bf16 v[58:61], v[158:161], v[182:185], v[58:61]
	v_mfma_f32_16x16x32_bf16 v[46:49], v[150:153], v[190:193], v[46:49]
	v_mfma_f32_16x16x32_bf16 v[42:45], v[158:161], v[190:193], v[42:45]
	v_mfma_f32_16x16x32_bf16 v[30:33], v[150:153], v[198:201], v[30:33]
	v_mfma_f32_16x16x32_bf16 v[26:29], v[158:161], v[198:201], v[26:29]
	v_mfma_f32_16x16x32_bf16 v[12:15], v[150:153], v[206:209], v[12:15]
	v_mfma_f32_16x16x32_bf16 v[8:11], v[158:161], v[206:209], v[8:11]
	v_mfma_f32_16x16x32_bf16 v[62:65], v[154:157], v[186:189], v[62:65]
	v_mfma_f32_16x16x32_bf16 v[58:61], v[162:165], v[186:189], v[58:61]
	v_mfma_f32_16x16x32_bf16 v[46:49], v[154:157], v[194:197], v[46:49]
	v_mfma_f32_16x16x32_bf16 v[42:45], v[162:165], v[194:197], v[42:45]
	v_mfma_f32_16x16x32_bf16 v[30:33], v[154:157], v[202:205], v[30:33]
	v_mfma_f32_16x16x32_bf16 v[26:29], v[162:165], v[202:205], v[26:29]
	v_mfma_f32_16x16x32_bf16 v[12:15], v[154:157], v[210:213], v[12:15]
	v_mfma_f32_16x16x32_bf16 v[8:11], v[162:165], v[210:213], v[8:11]
	v_mfma_f32_16x16x32_bf16 v[54:57], v[166:169], v[182:185], v[54:57]
	v_mfma_f32_16x16x32_bf16 v[50:53], v[174:177], v[182:185], v[50:53]
	v_mfma_f32_16x16x32_bf16 v[38:41], v[166:169], v[190:193], v[38:41]
	v_mfma_f32_16x16x32_bf16 v[34:37], v[174:177], v[190:193], v[34:37]
	v_mfma_f32_16x16x32_bf16 v[22:25], v[166:169], v[198:201], v[22:25]
	v_mfma_f32_16x16x32_bf16 v[18:21], v[174:177], v[198:201], v[18:21]
	v_mfma_f32_16x16x32_bf16 v[4:7], v[166:169], v[206:209], v[4:7]
	v_mfma_f32_16x16x32_bf16 v[0:3], v[174:177], v[206:209], v[0:3]
	v_mfma_f32_16x16x32_bf16 v[54:57], v[170:173], v[186:189], v[54:57]
	v_mfma_f32_16x16x32_bf16 v[50:53], v[178:181], v[186:189], v[50:53]
	v_mfma_f32_16x16x32_bf16 v[38:41], v[170:173], v[194:197], v[38:41]
	v_mfma_f32_16x16x32_bf16 v[34:37], v[178:181], v[194:197], v[34:37]
	v_mfma_f32_16x16x32_bf16 v[22:25], v[170:173], v[202:205], v[22:25]
	v_mfma_f32_16x16x32_bf16 v[18:21], v[178:181], v[202:205], v[18:21]
	v_mfma_f32_16x16x32_bf16 v[4:7], v[170:173], v[210:213], v[4:7]
	v_mfma_f32_16x16x32_bf16 v[0:3], v[178:181], v[210:213], v[0:3]
	s_barrier
	s_add_i32 s39, s39, 2
	s_add_u32 s40, s40, 0x100
	s_addc_u32 s41, s41, 0
	s_add_u32 s12, s12, 0x100
	s_addc_u32 s13, s13, 0
	s_cmp_gt_u32 s39, 61
	s_cbranch_scc0 .LBB0_712
	s_and_b64 vcc, exec, s[18:19]
	s_cbranch_vccz .LBB0_715
	s_barrier

; #define PG8_STAGEA(bufoff, gbase, voff) PG8_STAGE_X(bufoff, gbase, voff, AUXA)
; #define PG8_STAGEB(bufoff, gbase, voff) PG8_STAGE_X(bufoff, gbase, voff, AUXB)
; #define PG8_LDA(dst, b, h) do { _Pragma("unroll") for (int m = 0; m < 4; ++m) _Pragma("unroll") for (int k = 0; k < 2; ++k) dst[m][k] = *(const PG8_LAS bf16x8*)(lds + PG8_SA(b, h) + aoff + m * 2048 + k * 1024); } while (0)
; #define PG8_LDB(dst, b, h) do { _Pragma("unroll") for (int n = 0; n < 2; ++n) _Pragma("unroll") for (int k = 0; k < 2; ++k) dst[n][k] = *(const PG8_LAS bf16x8*)(lds + PG8_SB(b, h) + boff + n * 2048 + k * 1024); } while (0)
; #define PG8_MMA(ai, bj, At, Bt) do { if (GEMM_PRIO_MODE == 0) __builtin_amdgcn_s_setprio(1); PG8_MMA_LOOPS \
;         acc[ai][bj][m][n] = __builtin_amdgcn_mfma_f32_16x16x32_bf16(Bt[n][k], At[m][k], acc[ai][bj][m][n], 0, 0, 0); if (GEMM_PRIO_MODE == 0) __builtin_amdgcn_s_setprio(0); } while (0)
; #define PG8_WAIT_V(n) asm volatile("s_waitcnt vmcnt(" #n ")" ::: "memory")
; #define PG8_WAIT_VR(n, nr, flag) asm volatile("s_cmp_eq_u32 %0, 0\n\ts_cbranch_scc1 .Lpg8s%=\n\ts_waitcnt vmcnt(" #nr ")\n\ts_branch .Lpg8d%=\n.Lpg8s%=:\n\ts_waitcnt vmcnt(" #n ")\n.Lpg8d%=:" :: "s"(flag) : "memory", "scc")
; #define PG8_WAIT_L(n) asm volatile("s_waitcnt lgkmcnt(" #n ")" ::: "memory")
; #define PG8_BAR __builtin_amdgcn_s_barrier()
; #define PG8_SCHED __builtin_amdgcn_sched_barrier(0)
;     ...
;             PG8_LDB(B0, 0, 0); PG8_LDB(B1, 0, 1); PG8_SCHED; PG8_LDA(At, 0, 0); PG8_STAGEA(PG8_SA(1, 1), a1 + hstepA, voffA);
;     ...
;             const int relax = __builtin_amdgcn_readfirstlane((t == 0 && ui > 0) ? 1 : 0);
;             PG8_WAIT_VR(8, 24, relax); PG8_WAIT_L(0); PG8_BAR; PG8_MMA(0, 0, At, B0); PG8_MMA(0, 1, At, B1); PG8_BAR; PG8_SCHED;
;     ...
;             PG8_WAIT_V(8); PG8_WAIT_L(0); PG8_BAR; PG8_MMA(0, 0, At, B0); PG8_MMA(0, 1, At, B1); PG8_BAR; PG8_SCHED;
;     ...
;             PG8_LDA(At, 0, 1); PG8_STAGEB(PG8_SB(0, 0), b2, voffB); PG8_STAGEB(PG8_SB(0, 1), b2 + hstepB, voffB); PG8_STAGEA(PG8_SA(0, 0), a2, voffA);
;     ...
;             PG8_WAIT_VR(8, 24, relax); PG8_WAIT_L(0); PG8_BAR; PG8_MMA(1, 0, At, B0); PG8_MMA(1, 1, At, B1); PG8_BAR; PG8_SCHED;
;     ...
;             PG8_WAIT_V(8); PG8_WAIT_L(0); PG8_BAR; PG8_MMA(1, 0, At, B0); PG8_MMA(1, 1, At, B1); PG8_BAR; PG8_SCHED;
.LBB0_848:
	s_add_u32 s16, s24, 0x4000
	s_addc_u32 s17, s25, 0
	s_cmpk_eq_i32 s82, 0xfc
	s_cselect_b32 s36, s73, s16
	s_cselect_b32 s37, s11, s17
	s_cselect_b32 s16, s78, s0
	s_cselect_b32 s17, s15, s1
	s_add_u32 s26, s36, 0x8000
	s_addc_u32 s27, s37, 0
	s_add_i32 s83, 0, 0x10000
	s_add_i32 s94, 0, 0x14000
	s_add_i32 m0, s39, 0xc000
	ds_read_b128 v[130:133], v212
	global_load_lds_dwordx4 v144, s[24:25]
	s_add_i32 m0, s39, 0xe000
	ds_read_b128 v[134:137], v212 offset:1024
	global_load_lds_dwordx4 v146, s[24:25]
	ds_read_b128 v[148:151], v212 offset:2048
	ds_read_b128 v[152:155], v212 offset:3072
	ds_read_b128 v[162:165], v212 offset:16384
	ds_read_b128 v[166:169], v212 offset:17408
	ds_read_b128 v[170:173], v212 offset:18432
	ds_read_b128 v[174:177], v212 offset:19456
	ds_read_b128 v[178:181], v161
	ds_read_b128 v[182:185], v161 offset:1024
	ds_read_b128 v[186:189], v161 offset:2048
	ds_read_b128 v[190:193], v161 offset:3072
	ds_read_b128 v[194:197], v161 offset:4096
	ds_read_b128 v[198:201], v161 offset:5120
	ds_read_b128 v[202:205], v161 offset:6144
	ds_read_b128 v[206:209], v161 offset:7168
	s_waitcnt vmcnt(8) lgkmcnt(0)
	s_nop 0
	s_barrier
	v_mfma_f32_16x16x32_bf16 v[126:129], v[130:133], v[178:181], v[126:129]
	v_mfma_f32_16x16x32_bf16 v[122:125], v[148:151], v[178:181], v[122:125]
	v_mfma_f32_16x16x32_bf16 v[110:113], v[130:133], v[186:189], v[110:113]
	v_mfma_f32_16x16x32_bf16 v[106:109], v[148:151], v[186:189], v[106:109]
	v_mfma_f32_16x16x32_bf16 v[94:97], v[130:133], v[194:197], v[94:97]
	v_mfma_f32_16x16x32_bf16 v[90:93], v[148:151], v[194:197], v[90:93]
	v_mfma_f32_16x16x32_bf16 v[78:81], v[130:133], v[202:205], v[78:81]
	v_mfma_f32_16x16x32_bf16 v[74:77], v[148:151], v[202:205], v[74:77]
	v_mfma_f32_16x16x32_bf16 v[126:129], v[134:137], v[182:185], v[126:129]
	v_mfma_f32_16x16x32_bf16 v[122:125], v[152:155], v[182:185], v[122:125]
	v_mfma_f32_16x16x32_bf16 v[110:113], v[134:137], v[190:193], v[110:113]
	v_mfma_f32_16x16x32_bf16 v[106:109], v[152:155], v[190:193], v[106:109]
	v_mfma_f32_16x16x32_bf16 v[94:97], v[134:137], v[198:201], v[94:97]
	v_mfma_f32_16x16x32_bf16 v[90:93], v[152:155], v[198:201], v[90:93]
	v_mfma_f32_16x16x32_bf16 v[78:81], v[134:137], v[206:209], v[78:81]
	v_mfma_f32_16x16x32_bf16 v[74:77], v[152:155], v[206:209], v[74:77]
	v_mfma_f32_16x16x32_bf16 v[118:121], v[162:165], v[178:181], v[118:121]
	v_mfma_f32_16x16x32_bf16 v[114:117], v[170:173], v[178:181], v[114:117]
	v_mfma_f32_16x16x32_bf16 v[102:105], v[162:165], v[186:189], v[102:105]
	v_mfma_f32_16x16x32_bf16 v[98:101], v[170:173], v[186:189], v[98:101]
	v_mfma_f32_16x16x32_bf16 v[86:89], v[162:165], v[194:197], v[86:89]
	v_mfma_f32_16x16x32_bf16 v[82:85], v[170:173], v[194:197], v[82:85]
	v_mfma_f32_16x16x32_bf16 v[70:73], v[162:165], v[202:205], v[70:73]
	v_mfma_f32_16x16x32_bf16 v[66:69], v[170:173], v[202:205], v[66:69]
	v_mfma_f32_16x16x32_bf16 v[118:121], v[166:169], v[182:185], v[118:121]
	v_mfma_f32_16x16x32_bf16 v[114:117], v[174:177], v[182:185], v[114:117]
	v_mfma_f32_16x16x32_bf16 v[102:105], v[166:169], v[190:193], v[102:105]
	v_mfma_f32_16x16x32_bf16 v[98:101], v[174:177], v[190:193], v[98:101]
	v_mfma_f32_16x16x32_bf16 v[86:89], v[166:169], v[198:201], v[86:89]
	v_mfma_f32_16x16x32_bf16 v[82:85], v[174:177], v[198:201], v[82:85]
	v_mfma_f32_16x16x32_bf16 v[70:73], v[166:169], v[206:209], v[70:73]
	v_mfma_f32_16x16x32_bf16 v[66:69], v[174:177], v[206:209], v[66:69]
	s_barrier
	s_add_i32 s83, s83, s38
	s_mov_b32 m0, s83
	ds_read_b128 v[178:181], v161 offset:16384
	global_load_lds_dwordx4 v16, s[16:17]
	s_add_i32 m0, s83, 0x2000
	s_add_u32 s90, s16, 0x4000
	s_addc_u32 s91, s17, 0
	s_add_i32 s83, s94, s38
	global_load_lds_dwordx4 v138, s[16:17]
	s_mov_b32 m0, s83
	ds_read_b128 v[182:185], v161 offset:17408
	global_load_lds_dwordx4 v16, s[90:91]
	s_add_i32 m0, s83, 0x2000
	ds_read_b128 v[186:189], v161 offset:18432
	global_load_lds_dwordx4 v138, s[90:91]
	s_mov_b32 m0, s39
	ds_read_b128 v[190:193], v161 offset:19456
	global_load_lds_dwordx4 v142, s[36:37]
	s_mov_b32 m0, s40
	ds_read_b128 v[206:209], v161 offset:23552
	global_load_lds_dwordx4 v140, s[36:37]
	ds_read_b128 v[202:205], v161 offset:22528
	ds_read_b128 v[198:201], v161 offset:21504
	ds_read_b128 v[194:197], v161 offset:20480
	s_waitcnt vmcnt(8) lgkmcnt(0)
	s_barrier
	v_mfma_f32_16x16x32_bf16 v[62:65], v[130:133], v[178:181], v[62:65]
	v_mfma_f32_16x16x32_bf16 v[58:61], v[148:151], v[178:181], v[58:61]
	v_mfma_f32_16x16x32_bf16 v[46:49], v[130:133], v[186:189], v[46:49]
	v_mfma_f32_16x16x32_bf16 v[42:45], v[148:151], v[186:189], v[42:45]
	v_mfma_f32_16x16x32_bf16 v[30:33], v[130:133], v[194:197], v[30:33]
	v_mfma_f32_16x16x32_bf16 v[26:29], v[148:151], v[194:197], v[26:29]
	v_mfma_f32_16x16x32_bf16 v[12:15], v[130:133], v[202:205], v[12:15]
	v_mfma_f32_16x16x32_bf16 v[8:11], v[148:151], v[202:205], v[8:11]
	v_mfma_f32_16x16x32_bf16 v[62:65], v[134:137], v[182:185], v[62:65]
	v_mfma_f32_16x16x32_bf16 v[58:61], v[152:155], v[182:185], v[58:61]
	v_mfma_f32_16x16x32_bf16 v[46:49], v[134:137], v[190:193], v[46:49]
	v_mfma_f32_16x16x32_bf16 v[42:45], v[152:155], v[190:193], v[42:45]
	v_mfma_f32_16x16x32_bf16 v[30:33], v[134:137], v[198:201], v[30:33]
	v_mfma_f32_16x16x32_bf16 v[26:29], v[152:155], v[198:201], v[26:29]
	v_mfma_f32_16x16x32_bf16 v[12:15], v[134:137], v[206:209], v[12:15]
	v_mfma_f32_16x16x32_bf16 v[8:11], v[152:155], v[206:209], v[8:11]
	v_mfma_f32_16x16x32_bf16 v[54:57], v[162:165], v[178:181], v[54:57]
	v_mfma_f32_16x16x32_bf16 v[50:53], v[170:173], v[178:181], v[50:53]
	v_mfma_f32_16x16x32_bf16 v[38:41], v[162:165], v[186:189], v[38:41]
	v_mfma_f32_16x16x32_bf16 v[34:37], v[170:173], v[186:189], v[34:37]
	v_mfma_f32_16x16x32_bf16 v[22:25], v[162:165], v[194:197], v[22:25]
	v_mfma_f32_16x16x32_bf16 v[18:21], v[170:173], v[194:197], v[18:21]
	v_mfma_f32_16x16x32_bf16 v[4:7], v[162:165], v[202:205], v[4:7]
	v_mfma_f32_16x16x32_bf16 v[0:3], v[170:173], v[202:205], v[0:3]
	v_mfma_f32_16x16x32_bf16 v[54:57], v[166:169], v[182:185], v[54:57]
	v_mfma_f32_16x16x32_bf16 v[50:53], v[174:177], v[182:185], v[50:53]
	v_mfma_f32_16x16x32_bf16 v[38:41], v[166:169], v[190:193], v[38:41]
	v_mfma_f32_16x16x32_bf16 v[34:37], v[174:177], v[190:193], v[34:37]
	v_mfma_f32_16x16x32_bf16 v[22:25], v[166:169], v[198:201], v[22:25]
	v_mfma_f32_16x16x32_bf16 v[18:21], v[174:177], v[198:201], v[18:21]
	v_mfma_f32_16x16x32_bf16 v[4:7], v[166:169], v[206:209], v[4:7]
	v_mfma_f32_16x16x32_bf16 v[0:3], v[174:177], v[206:209], v[0:3]
	s_barrier
; #define PG8_STAGEA(bufoff, gbase, voff) PG8_STAGE_X(bufoff, gbase, voff, AUXA)
; #define PG8_STAGEB(bufoff, gbase, voff) PG8_STAGE_X(bufoff, gbase, voff, AUXB)
; #define PG8_LDA(dst, b, h) do { _Pragma("unroll") for (int m = 0; m < 4; ++m) _Pragma("unroll") for (int k = 0; k < 2; ++k) dst[m][k] = *(const PG8_LAS bf16x8*)(lds + PG8_SA(b, h) + aoff + m * 2048 + k * 1024); } while (0)
; #define PG8_LDB(dst, b, h) do { _Pragma("unroll") for (int n = 0; n < 2; ++n) _Pragma("unroll") for (int k = 0; k < 2; ++k) dst[n][k] = *(const PG8_LAS bf16x8*)(lds + PG8_SB(b, h) + boff + n * 2048 + k * 1024); } while (0)
; #define PG8_MMA(ai, bj, At, Bt) do { if (GEMM_PRIO_MODE == 0) __builtin_amdgcn_s_setprio(1); PG8_MMA_LOOPS \
;         acc[ai][bj][m][n] = __builtin_amdgcn_mfma_f32_16x16x32_bf16(Bt[n][k], At[m][k], acc[ai][bj][m][n], 0, 0, 0); if (GEMM_PRIO_MODE == 0) __builtin_amdgcn_s_setprio(0); } while (0)
; #define PG8_WAIT_V(n) asm volatile("s_waitcnt vmcnt(" #n ")" ::: "memory")
; #define PG8_WAIT_L(n) asm volatile("s_waitcnt lgkmcnt(" #n ")" ::: "memory")
; #define PG8_BAR __builtin_amdgcn_s_barrier()
; #define PG8_SCHED __builtin_amdgcn_sched_barrier(0)
;     ...
;             PG8_LDB(B0, 1, 0); PG8_LDB(B1, 1, 1); PG8_SCHED; PG8_LDA(At, 1, 0); PG8_STAGEA(PG8_SA(0, 1), a2 + hstepA, voffA);
;             PG8_WAIT_V(8); PG8_WAIT_L(0); PG8_BAR; PG8_MMA(0, 0, At, B0); PG8_MMA(0, 1, At, B1); PG8_BAR; PG8_SCHED;
;             PG8_LDA(At, 1, 1); PG8_STAGEB(PG8_SB(1, 0), b3, voffB); PG8_STAGEB(PG8_SB(1, 1), b3 + hstepB, voffB); PG8_STAGEA(PG8_SA(1, 0), a3, voffA);
;             PG8_WAIT_V(8); PG8_WAIT_L(0); PG8_BAR; PG8_MMA(1, 0, At, B0); PG8_MMA(1, 1, At, B1); PG8_BAR; PG8_SCHED;
	s_add_i32 s83, 0, 0x18000
	s_add_i32 s90, 0, 0x1c000
	s_add_u32 s36, s36, 0x4000
	s_addc_u32 s37, s37, 0
	s_mov_b32 m0, s41
	ds_read_b128 v[130:133], v212 offset:32768
	global_load_lds_dwordx4 v142, s[36:37]
	s_mov_b32 m0, s42
	ds_read_b128 v[134:137], v212 offset:33792
	global_load_lds_dwordx4 v140, s[36:37]
	ds_read_b128 v[148:151], v212 offset:34816
	ds_read_b128 v[152:155], v212 offset:35840
	ds_read_b128 v[162:165], v212 offset:49152
	ds_read_b128 v[166:169], v212 offset:50176
	ds_read_b128 v[170:173], v212 offset:51200
	ds_read_b128 v[174:177], v212 offset:52224
	ds_read_b128 v[178:181], v161 offset:32768
	ds_read_b128 v[182:185], v161 offset:33792
	ds_read_b128 v[186:189], v161 offset:34816
	ds_read_b128 v[190:193], v161 offset:35840
	ds_read_b128 v[194:197], v161 offset:36864
	ds_read_b128 v[198:201], v161 offset:37888
	ds_read_b128 v[202:205], v161 offset:38912
	ds_read_b128 v[206:209], v161 offset:39936
	s_waitcnt vmcnt(8) lgkmcnt(0)
	s_barrier
	v_mfma_f32_16x16x32_bf16 v[126:129], v[130:133], v[178:181], v[126:129]
	v_mfma_f32_16x16x32_bf16 v[122:125], v[148:151], v[178:181], v[122:125]
	v_mfma_f32_16x16x32_bf16 v[110:113], v[130:133], v[186:189], v[110:113]
	v_mfma_f32_16x16x32_bf16 v[106:109], v[148:151], v[186:189], v[106:109]
	v_mfma_f32_16x16x32_bf16 v[94:97], v[130:133], v[194:197], v[94:97]
	v_mfma_f32_16x16x32_bf16 v[90:93], v[148:151], v[194:197], v[90:93]
	v_mfma_f32_16x16x32_bf16 v[78:81], v[130:133], v[202:205], v[78:81]
	v_mfma_f32_16x16x32_bf16 v[74:77], v[148:151], v[202:205], v[74:77]
	v_mfma_f32_16x16x32_bf16 v[126:129], v[134:137], v[182:185], v[126:129]
	v_mfma_f32_16x16x32_bf16 v[122:125], v[152:155], v[182:185], v[122:125]
	v_mfma_f32_16x16x32_bf16 v[110:113], v[134:137], v[190:193], v[110:113]
	v_mfma_f32_16x16x32_bf16 v[106:109], v[152:155], v[190:193], v[106:109]
	v_mfma_f32_16x16x32_bf16 v[94:97], v[134:137], v[198:201], v[94:97]
	v_mfma_f32_16x16x32_bf16 v[90:93], v[152:155], v[198:201], v[90:93]
	v_mfma_f32_16x16x32_bf16 v[78:81], v[134:137], v[206:209], v[78:81]
	v_mfma_f32_16x16x32_bf16 v[74:77], v[152:155], v[206:209], v[74:77]
	v_mfma_f32_16x16x32_bf16 v[118:121], v[162:165], v[178:181], v[118:121]
	v_mfma_f32_16x16x32_bf16 v[114:117], v[170:173], v[178:181], v[114:117]
	v_mfma_f32_16x16x32_bf16 v[102:105], v[162:165], v[186:189], v[102:105]
	v_mfma_f32_16x16x32_bf16 v[98:101], v[170:173], v[186:189], v[98:101]
	v_mfma_f32_16x16x32_bf16 v[86:89], v[162:165], v[194:197], v[86:89]
	v_mfma_f32_16x16x32_bf16 v[82:85], v[170:173], v[194:197], v[82:85]
	v_mfma_f32_16x16x32_bf16 v[70:73], v[162:165], v[202:205], v[70:73]
	v_mfma_f32_16x16x32_bf16 v[66:69], v[170:173], v[202:205], v[66:69]
	v_mfma_f32_16x16x32_bf16 v[118:121], v[166:169], v[182:185], v[118:121]
	v_mfma_f32_16x16x32_bf16 v[114:117], v[174:177], v[182:185], v[114:117]
	v_mfma_f32_16x16x32_bf16 v[102:105], v[166:169], v[190:193], v[102:105]
	v_mfma_f32_16x16x32_bf16 v[98:101], v[174:177], v[190:193], v[98:101]
	v_mfma_f32_16x16x32_bf16 v[86:89], v[166:169], v[198:201], v[86:89]
	v_mfma_f32_16x16x32_bf16 v[82:85], v[174:177], v[198:201], v[82:85]
	v_mfma_f32_16x16x32_bf16 v[70:73], v[166:169], v[206:209], v[70:73]
	v_mfma_f32_16x16x32_bf16 v[66:69], v[174:177], v[206:209], v[66:69]
	s_barrier
	s_add_u32 s36, s16, 0x8000
	s_addc_u32 s37, s17, 0
	s_add_i32 s83, s83, s38
	s_mov_b32 m0, s83
	ds_read_b128 v[178:181], v161 offset:49152
	global_load_lds_dwordx4 v16, s[36:37]
	s_add_i32 m0, s83, 0x2000
	s_add_u32 s16, s16, 0xc000
	s_addc_u32 s17, s17, 0
	global_load_lds_dwordx4 v138, s[36:37]
	s_add_i32 s36, s90, s38
	s_mov_b32 m0, s36
	ds_read_b128 v[182:185], v161 offset:50176
	global_load_lds_dwordx4 v16, s[16:17]
	s_add_i32 m0, s36, 0x2000
	ds_read_b128 v[186:189], v161 offset:51200
	global_load_lds_dwordx4 v138, s[16:17]
	s_mov_b32 m0, s50
	ds_read_b128 v[190:193], v161 offset:52224
	global_load_lds_dwordx4 v142, s[26:27]
	s_mov_b32 m0, s51
	ds_read_b128 v[206:209], v161 offset:56320
	global_load_lds_dwordx4 v140, s[26:27]
	ds_read_b128 v[202:205], v161 offset:55296
	ds_read_b128 v[198:201], v161 offset:54272
	ds_read_b128 v[194:197], v161 offset:53248
	s_waitcnt vmcnt(8) lgkmcnt(0)
	s_nop 0
	s_barrier
	v_mfma_f32_16x16x32_bf16 v[62:65], v[130:133], v[178:181], v[62:65]
	v_mfma_f32_16x16x32_bf16 v[58:61], v[148:151], v[178:181], v[58:61]
	v_mfma_f32_16x16x32_bf16 v[46:49], v[130:133], v[186:189], v[46:49]
	v_mfma_f32_16x16x32_bf16 v[42:45], v[148:151], v[186:189], v[42:45]
	v_mfma_f32_16x16x32_bf16 v[30:33], v[130:133], v[194:197], v[30:33]
	v_mfma_f32_16x16x32_bf16 v[26:29], v[148:151], v[194:197], v[26:29]
	v_mfma_f32_16x16x32_bf16 v[12:15], v[130:133], v[202:205], v[12:15]
	v_mfma_f32_16x16x32_bf16 v[8:11], v[148:151], v[202:205], v[8:11]
	v_mfma_f32_16x16x32_bf16 v[62:65], v[134:137], v[182:185], v[62:65]
	v_mfma_f32_16x16x32_bf16 v[58:61], v[152:155], v[182:185], v[58:61]
	v_mfma_f32_16x16x32_bf16 v[46:49], v[134:137], v[190:193], v[46:49]
	v_mfma_f32_16x16x32_bf16 v[42:45], v[152:155], v[190:193], v[42:45]
	v_mfma_f32_16x16x32_bf16 v[30:33], v[134:137], v[198:201], v[30:33]
	v_mfma_f32_16x16x32_bf16 v[26:29], v[152:155], v[198:201], v[26:29]
	v_mfma_f32_16x16x32_bf16 v[12:15], v[134:137], v[206:209], v[12:15]
	v_mfma_f32_16x16x32_bf16 v[8:11], v[152:155], v[206:209], v[8:11]
	v_mfma_f32_16x16x32_bf16 v[54:57], v[162:165], v[178:181], v[54:57]
	v_mfma_f32_16x16x32_bf16 v[50:53], v[170:173], v[178:181], v[50:53]
	v_mfma_f32_16x16x32_bf16 v[38:41], v[162:165], v[186:189], v[38:41]
	v_mfma_f32_16x16x32_bf16 v[34:37], v[170:173], v[186:189], v[34:37]
	v_mfma_f32_16x16x32_bf16 v[22:25], v[162:165], v[194:197], v[22:25]
	v_mfma_f32_16x16x32_bf16 v[18:21], v[170:173], v[194:197], v[18:21]
	v_mfma_f32_16x16x32_bf16 v[4:7], v[162:165], v[202:205], v[4:7]
	v_mfma_f32_16x16x32_bf16 v[0:3], v[170:173], v[202:205], v[0:3]
	v_mfma_f32_16x16x32_bf16 v[54:57], v[166:169], v[182:185], v[54:57]
	v_mfma_f32_16x16x32_bf16 v[50:53], v[174:177], v[182:185], v[50:53]
	v_mfma_f32_16x16x32_bf16 v[38:41], v[166:169], v[190:193], v[38:41]
	v_mfma_f32_16x16x32_bf16 v[34:37], v[174:177], v[190:193], v[34:37]
	v_mfma_f32_16x16x32_bf16 v[22:25], v[166:169], v[198:201], v[22:25]
	v_mfma_f32_16x16x32_bf16 v[18:21], v[174:177], v[198:201], v[18:21]
	v_mfma_f32_16x16x32_bf16 v[4:7], v[166:169], v[206:209], v[4:7]
	v_mfma_f32_16x16x32_bf16 v[0:3], v[174:177], v[206:209], v[0:3]
	s_barrier
	s_add_i32 s82, s82, 2
	s_add_u32 s24, s24, 0x10000
	s_addc_u32 s25, s25, 0
	s_add_u32 s0, s0, 0x10000
	s_addc_u32 s1, s1, 0
	s_cmpk_gt_u32 s82, 0xfd
	s_cbranch_scc0 .LBB0_848
	s_and_b64 vcc, exec, s[8:9]
	s_cbranch_vccz .LBB0_851
	s_barrier
